# P0: LN row loop with gamma/beta hoisted + next-row prefetch; weight-transpose items issue all 32 loads before LDS writes (P0 and HGRN pass-1 idle WGs)
# speedup vs baseline: 1.0181x; 1.0138x over previous
.LBB0_31:
	v_lshl_add_u64 v[60:61], v[44:45], 0, s[4:5]
	v_lshl_add_u64 v[62:63], v[42:43], 0, s[4:5]
	v_lshl_add_u64 v[64:65], v[40:41], 0, s[4:5]
	v_lshl_add_u64 v[66:67], v[38:39], 0, s[4:5]
	v_lshl_add_u64 v[68:69], v[36:37], 0, s[4:5]
	v_lshl_add_u64 v[70:71], v[34:35], 0, s[4:5]
	v_lshl_add_u64 v[72:73], v[32:33], 0, s[4:5]
	v_lshl_add_u64 v[74:75], v[30:31], 0, s[4:5]
	global_load_dword v128, v[60:61], off nt
	s_nop 0
	global_load_dword v129, v[62:63], off nt
	global_load_dword v130, v[64:65], off nt
	s_nop 0
	global_load_dword v131, v[66:67], off nt
	global_load_dword v132, v[68:69], off nt
	global_load_dword v133, v[70:71], off nt
	global_load_dword v134, v[72:73], off nt
	s_nop 0
	global_load_dword v135, v[74:75], off nt
	s_add_u32 s4, s4, 0x10000
	s_addc_u32 s5, s5, 0
	v_lshl_add_u64 v[60:61], v[44:45], 0, s[4:5]
	v_lshl_add_u64 v[62:63], v[42:43], 0, s[4:5]
	v_lshl_add_u64 v[64:65], v[40:41], 0, s[4:5]
	v_lshl_add_u64 v[66:67], v[38:39], 0, s[4:5]
	v_lshl_add_u64 v[68:69], v[36:37], 0, s[4:5]
	v_lshl_add_u64 v[70:71], v[34:35], 0, s[4:5]
	v_lshl_add_u64 v[72:73], v[32:33], 0, s[4:5]
	v_lshl_add_u64 v[74:75], v[30:31], 0, s[4:5]
	global_load_dword v136, v[60:61], off nt
	s_nop 0
	global_load_dword v137, v[62:63], off nt
	global_load_dword v138, v[64:65], off nt
	s_nop 0
	global_load_dword v139, v[66:67], off nt
	global_load_dword v140, v[68:69], off nt
	global_load_dword v141, v[70:71], off nt
	global_load_dword v142, v[72:73], off nt
	s_nop 0
	global_load_dword v143, v[74:75], off nt
	s_add_u32 s4, s4, 0x10000
	s_addc_u32 s5, s5, 0
	v_lshl_add_u64 v[60:61], v[44:45], 0, s[4:5]
	v_lshl_add_u64 v[62:63], v[42:43], 0, s[4:5]
	v_lshl_add_u64 v[64:65], v[40:41], 0, s[4:5]
	v_lshl_add_u64 v[66:67], v[38:39], 0, s[4:5]
	v_lshl_add_u64 v[68:69], v[36:37], 0, s[4:5]
	v_lshl_add_u64 v[70:71], v[34:35], 0, s[4:5]
	v_lshl_add_u64 v[72:73], v[32:33], 0, s[4:5]
	v_lshl_add_u64 v[74:75], v[30:31], 0, s[4:5]
	global_load_dword v144, v[60:61], off nt
	s_nop 0
	global_load_dword v145, v[62:63], off nt
	global_load_dword v146, v[64:65], off nt
	s_nop 0
	global_load_dword v147, v[66:67], off nt
	global_load_dword v148, v[68:69], off nt
	global_load_dword v149, v[70:71], off nt
	global_load_dword v150, v[72:73], off nt
	s_nop 0
	global_load_dword v151, v[74:75], off nt
	s_add_u32 s4, s4, 0x10000
	s_addc_u32 s5, s5, 0
	v_lshl_add_u64 v[60:61], v[44:45], 0, s[4:5]
	v_lshl_add_u64 v[62:63], v[42:43], 0, s[4:5]
	v_lshl_add_u64 v[64:65], v[40:41], 0, s[4:5]
	v_lshl_add_u64 v[66:67], v[38:39], 0, s[4:5]
	v_lshl_add_u64 v[68:69], v[36:37], 0, s[4:5]
	v_lshl_add_u64 v[70:71], v[34:35], 0, s[4:5]
	v_lshl_add_u64 v[72:73], v[32:33], 0, s[4:5]
	v_lshl_add_u64 v[74:75], v[30:31], 0, s[4:5]
	global_load_dword v152, v[60:61], off nt
	s_nop 0
	global_load_dword v153, v[62:63], off nt
	global_load_dword v154, v[64:65], off nt
	s_nop 0
	global_load_dword v155, v[66:67], off nt
	global_load_dword v156, v[68:69], off nt
	global_load_dword v157, v[70:71], off nt
	global_load_dword v158, v[72:73], off nt
	s_nop 0
	global_load_dword v159, v[74:75], off nt
	s_add_u32 s4, s4, 0x10000
	s_addc_u32 s5, s5, 0
	v_add_u32_e32 v67, 0x400, v0
	s_waitcnt vmcnt(30)
	ds_write2_b32 v0, v128, v129 offset1:66
	s_waitcnt vmcnt(28)
	ds_write2_b32 v0, v130, v131 offset0:132 offset1:198
	s_waitcnt vmcnt(26)
	ds_write2_b32 v67, v132, v133 offset0:8 offset1:74
	s_waitcnt vmcnt(24)
	ds_write2_b32 v67, v134, v135 offset0:140 offset1:206
	v_add_u32_e32 v0, 0x840, v0
	v_add_u32_e32 v67, 0x400, v0
	s_waitcnt vmcnt(22)
	ds_write2_b32 v0, v136, v137 offset1:66
	s_waitcnt vmcnt(20)
	ds_write2_b32 v0, v138, v139 offset0:132 offset1:198
	s_waitcnt vmcnt(18)
	ds_write2_b32 v67, v140, v141 offset0:8 offset1:74
	s_waitcnt vmcnt(16)
	ds_write2_b32 v67, v142, v143 offset0:140 offset1:206
	v_add_u32_e32 v0, 0x840, v0
	v_add_u32_e32 v67, 0x400, v0
	s_waitcnt vmcnt(14)
	ds_write2_b32 v0, v144, v145 offset1:66
	s_waitcnt vmcnt(12)
	ds_write2_b32 v0, v146, v147 offset0:132 offset1:198
	s_waitcnt vmcnt(10)
	ds_write2_b32 v67, v148, v149 offset0:8 offset1:74
	s_waitcnt vmcnt(8)
	ds_write2_b32 v67, v150, v151 offset0:140 offset1:206
	v_add_u32_e32 v0, 0x840, v0
	v_add_u32_e32 v67, 0x400, v0
	s_waitcnt vmcnt(6)
	ds_write2_b32 v0, v152, v153 offset1:66
	s_waitcnt vmcnt(4)
	ds_write2_b32 v0, v154, v155 offset0:132 offset1:198
	s_waitcnt vmcnt(2)
	ds_write2_b32 v67, v156, v157 offset0:8 offset1:74
	s_waitcnt vmcnt(0)
	ds_write2_b32 v67, v158, v159 offset0:140 offset1:206
	v_add_u32_e32 v0, 0x840, v0
	s_lshl_b32 s0, s19, 1
	s_lshl_b32 s4, s19, 5
	s_waitcnt lgkmcnt(0)
	s_add_i32 s0, s0, 0x7fffb200
	s_and_b32 s4, s4, 0x3e0
	ds_read2_b32 v[34:35], v46 offset0:33 offset1:41
	ds_read2_b32 v[36:37], v46 offset1:8
	ds_read2_b32 v[38:39], v46 offset0:66 offset1:74
	ds_read2_b32 v[40:41], v46 offset0:99 offset1:107
	ds_read2_b32 v[42:43], v46 offset0:132 offset1:140
	ds_read2_b32 v[44:45], v46 offset0:165 offset1:173
	ds_read2_b32 v[60:61], v46 offset0:198 offset1:206
	ds_read2_b32 v[62:63], v46 offset0:231 offset1:239
	s_and_b32 s0, s0, 0x7fffffc0
	v_or_b32_e32 v0, s4, v3
	s_lshl_b32 s0, s0, 1
	v_mul_u32_u24_e32 v0, 0xb00, v0
	v_lshl_add_u64 v[64:65], v[4:5], 0, s[0:1]
	v_lshlrev_b32_e32 v0, 1, v0
	v_lshl_add_u64 v[66:67], v[64:65], 0, v[0:1]
	v_or_b32_e32 v0, s4, v47
	s_waitcnt lgkmcnt(6)
	v_cvt_pk_bf16_f32 v30, v36, v34
	s_waitcnt lgkmcnt(4)
	v_cvt_pk_bf16_f32 v31, v38, v40
	s_waitcnt lgkmcnt(2)
	v_cvt_pk_bf16_f32 v32, v42, v44
	s_waitcnt lgkmcnt(0)
	v_cvt_pk_bf16_f32 v33, v60, v62
	v_mul_u32_u24_e32 v0, 0xb00, v0
	global_store_dwordx4 v[66:67], v[30:33], off
	v_lshlrev_b32_e32 v0, 1, v0
	s_nop 0
	v_cvt_pk_bf16_f32 v30, v37, v35
	v_cvt_pk_bf16_f32 v31, v39, v41
	v_cvt_pk_bf16_f32 v32, v43, v45
	v_cvt_pk_bf16_f32 v33, v61, v63
	v_lshl_add_u64 v[34:35], v[64:65], 0, v[0:1]
	ds_read2_b32 v[36:37], v46 offset0:16 offset1:24
	ds_read2_b32 v[38:39], v46 offset0:49 offset1:57
	ds_read2_b32 v[40:41], v46 offset0:82 offset1:90
	ds_read2_b32 v[42:43], v46 offset0:115 offset1:123
	ds_read2_b32 v[44:45], v46 offset0:148 offset1:156
	ds_read2_b32 v[60:61], v46 offset0:181 offset1:189
	ds_read2_b32 v[62:63], v46 offset0:214 offset1:222
	ds_read2_b32 v[66:67], v46 offset0:247 offset1:255
	v_or_b32_e32 v0, s4, v48
	v_mul_u32_u24_e32 v0, 0xb00, v0
	v_lshlrev_b32_e32 v0, 1, v0
	global_store_dwordx4 v[34:35], v[30:33], off
	v_lshl_add_u64 v[34:35], v[64:65], 0, v[0:1]
	v_or_b32_e32 v0, s4, v49
	v_mul_u32_u24_e32 v0, 0xb00, v0
	s_waitcnt lgkmcnt(6)
	v_cvt_pk_bf16_f32 v30, v36, v38
	s_waitcnt lgkmcnt(4)
	v_cvt_pk_bf16_f32 v31, v40, v42
	s_waitcnt lgkmcnt(2)
	v_cvt_pk_bf16_f32 v32, v44, v60
	s_waitcnt lgkmcnt(0)
	v_cvt_pk_bf16_f32 v33, v62, v66
	v_lshlrev_b32_e32 v0, 1, v0
	global_store_dwordx4 v[34:35], v[30:33], off
	v_lshl_add_u64 v[34:35], v[64:65], 0, v[0:1]
	s_mov_b64 s[4:5], 0
	v_cvt_pk_bf16_f32 v30, v37, v39
	v_cvt_pk_bf16_f32 v31, v41, v43
	v_cvt_pk_bf16_f32 v32, v45, v61
	v_cvt_pk_bf16_f32 v33, v63, v67
	global_store_dwordx4 v[34:35], v[30:33], off
	s_waitcnt lgkmcnt(0)

.LBB0_35:
	v_lshl_add_u64 v[40:41], v[38:39], 0, s[4:5]
	v_add_co_u32_e32 v64, vcc, 0xb000, v40
	global_load_dword v128, v[40:41], off nt
	s_nop 0
	v_addc_co_u32_e32 v65, vcc, 0, v41, vcc
	v_add_co_u32_e32 v66, vcc, 0x16000, v40
	global_load_dword v129, v[64:65], off nt
	s_nop 0
	v_addc_co_u32_e32 v67, vcc, 0, v41, vcc
	v_add_co_u32_e32 v40, vcc, 0x21000, v40
	v_lshl_add_u64 v[42:43], v[36:37], 0, s[4:5]
	v_lshl_add_u64 v[44:45], v[34:35], 0, s[4:5]
	v_addc_co_u32_e32 v41, vcc, 0, v41, vcc
	v_lshl_add_u64 v[60:61], v[32:33], 0, s[4:5]
	v_lshl_add_u64 v[62:63], v[30:31], 0, s[4:5]
	global_load_dword v130, v[66:67], off nt
	s_nop 0
	global_load_dword v131, v[40:41], off nt
	s_nop 0
	global_load_dword v132, v[42:43], off nt
	s_nop 0
	global_load_dword v133, v[44:45], off nt
	global_load_dword v134, v[60:61], off nt
	s_nop 0
	global_load_dword v135, v[62:63], off nt
	s_add_u32 s4, s4, 0x58000
	s_addc_u32 s5, s5, 0
	v_lshl_add_u64 v[40:41], v[38:39], 0, s[4:5]
	v_add_co_u32_e32 v64, vcc, 0xb000, v40
	global_load_dword v136, v[40:41], off nt
	s_nop 0
	v_addc_co_u32_e32 v65, vcc, 0, v41, vcc
	v_add_co_u32_e32 v66, vcc, 0x16000, v40
	global_load_dword v137, v[64:65], off nt
	s_nop 0
	v_addc_co_u32_e32 v67, vcc, 0, v41, vcc
	v_add_co_u32_e32 v40, vcc, 0x21000, v40
	v_lshl_add_u64 v[42:43], v[36:37], 0, s[4:5]
	v_lshl_add_u64 v[44:45], v[34:35], 0, s[4:5]
	v_addc_co_u32_e32 v41, vcc, 0, v41, vcc
	v_lshl_add_u64 v[60:61], v[32:33], 0, s[4:5]
	v_lshl_add_u64 v[62:63], v[30:31], 0, s[4:5]
	global_load_dword v138, v[66:67], off nt
	s_nop 0
	global_load_dword v139, v[40:41], off nt
	s_nop 0
	global_load_dword v140, v[42:43], off nt
	s_nop 0
	global_load_dword v141, v[44:45], off nt
	global_load_dword v142, v[60:61], off nt
	s_nop 0
	global_load_dword v143, v[62:63], off nt
	s_add_u32 s4, s4, 0x58000
	s_addc_u32 s5, s5, 0
	v_lshl_add_u64 v[40:41], v[38:39], 0, s[4:5]
	v_add_co_u32_e32 v64, vcc, 0xb000, v40
	global_load_dword v144, v[40:41], off nt
	s_nop 0
	v_addc_co_u32_e32 v65, vcc, 0, v41, vcc
	v_add_co_u32_e32 v66, vcc, 0x16000, v40
	global_load_dword v145, v[64:65], off nt
	s_nop 0
	v_addc_co_u32_e32 v67, vcc, 0, v41, vcc
	v_add_co_u32_e32 v40, vcc, 0x21000, v40
	v_lshl_add_u64 v[42:43], v[36:37], 0, s[4:5]
	v_lshl_add_u64 v[44:45], v[34:35], 0, s[4:5]
	v_addc_co_u32_e32 v41, vcc, 0, v41, vcc
	v_lshl_add_u64 v[60:61], v[32:33], 0, s[4:5]
	v_lshl_add_u64 v[62:63], v[30:31], 0, s[4:5]
	global_load_dword v146, v[66:67], off nt
	s_nop 0
	global_load_dword v147, v[40:41], off nt
	s_nop 0
	global_load_dword v148, v[42:43], off nt
	s_nop 0
	global_load_dword v149, v[44:45], off nt
	global_load_dword v150, v[60:61], off nt
	s_nop 0
	global_load_dword v151, v[62:63], off nt
	s_add_u32 s4, s4, 0x58000
	s_addc_u32 s5, s5, 0
	v_lshl_add_u64 v[40:41], v[38:39], 0, s[4:5]
	v_add_co_u32_e32 v64, vcc, 0xb000, v40
	global_load_dword v152, v[40:41], off nt
	s_nop 0
	v_addc_co_u32_e32 v65, vcc, 0, v41, vcc
	v_add_co_u32_e32 v66, vcc, 0x16000, v40
	global_load_dword v153, v[64:65], off nt
	s_nop 0
	v_addc_co_u32_e32 v67, vcc, 0, v41, vcc
	v_add_co_u32_e32 v40, vcc, 0x21000, v40
	v_lshl_add_u64 v[42:43], v[36:37], 0, s[4:5]
	v_lshl_add_u64 v[44:45], v[34:35], 0, s[4:5]
	v_addc_co_u32_e32 v41, vcc, 0, v41, vcc
	v_lshl_add_u64 v[60:61], v[32:33], 0, s[4:5]
	v_lshl_add_u64 v[62:63], v[30:31], 0, s[4:5]
	global_load_dword v154, v[66:67], off nt
	s_nop 0
	global_load_dword v155, v[40:41], off nt
	s_nop 0
	global_load_dword v156, v[42:43], off nt
	s_nop 0
	global_load_dword v157, v[44:45], off nt
	global_load_dword v158, v[60:61], off nt
	s_nop 0
	global_load_dword v159, v[62:63], off nt
	s_add_u32 s4, s4, 0x58000
	s_addc_u32 s5, s5, 0
	v_add_u32_e32 v45, 0x400, v0
	s_waitcnt vmcnt(30)
	ds_write2_b32 v0, v128, v129 offset1:66
	s_waitcnt vmcnt(28)
	ds_write2_b32 v0, v130, v131 offset0:132 offset1:198
	s_waitcnt vmcnt(26)
	ds_write2_b32 v45, v132, v133 offset0:8 offset1:74
	s_waitcnt vmcnt(24)
	ds_write2_b32 v45, v134, v135 offset0:140 offset1:206
	v_add_u32_e32 v0, 0x840, v0
	v_add_u32_e32 v45, 0x400, v0
	s_waitcnt vmcnt(22)
	ds_write2_b32 v0, v136, v137 offset1:66
	s_waitcnt vmcnt(20)
	ds_write2_b32 v0, v138, v139 offset0:132 offset1:198
	s_waitcnt vmcnt(18)
	ds_write2_b32 v45, v140, v141 offset0:8 offset1:74
	s_waitcnt vmcnt(16)
	ds_write2_b32 v45, v142, v143 offset0:140 offset1:206
	v_add_u32_e32 v0, 0x840, v0
	v_add_u32_e32 v45, 0x400, v0
	s_waitcnt vmcnt(14)
	ds_write2_b32 v0, v144, v145 offset1:66
	s_waitcnt vmcnt(12)
	ds_write2_b32 v0, v146, v147 offset0:132 offset1:198
	s_waitcnt vmcnt(10)
	ds_write2_b32 v45, v148, v149 offset0:8 offset1:74
	s_waitcnt vmcnt(8)
	ds_write2_b32 v45, v150, v151 offset0:140 offset1:206
	v_add_u32_e32 v0, 0x840, v0
	v_add_u32_e32 v45, 0x400, v0
	s_waitcnt vmcnt(6)
	ds_write2_b32 v0, v152, v153 offset1:66
	s_waitcnt vmcnt(4)
	ds_write2_b32 v0, v154, v155 offset0:132 offset1:198
	s_waitcnt vmcnt(2)
	ds_write2_b32 v45, v156, v157 offset0:8 offset1:74
	s_waitcnt vmcnt(0)
	ds_write2_b32 v45, v158, v159 offset0:140 offset1:206
	v_add_u32_e32 v0, 0x840, v0
	s_waitcnt lgkmcnt(0)
	ds_read2_b32 v[34:35], v46 offset0:33 offset1:41
	ds_read2_b32 v[36:37], v46 offset1:8
	ds_read2_b32 v[38:39], v46 offset0:66 offset1:74
	ds_read2_b32 v[40:41], v46 offset0:99 offset1:107
	ds_read2_b32 v[42:43], v46 offset0:132 offset1:140
	ds_read2_b32 v[44:45], v46 offset0:165 offset1:173
	ds_read2_b32 v[60:61], v46 offset0:198 offset1:206
	ds_read2_b32 v[62:63], v46 offset0:231 offset1:239
	s_and_b32 s0, 0xffff, s8
	s_lshl_b32 s0, s0, 1
	v_or_b32_e32 v0, s7, v3
	v_lshl_add_u64 v[64:65], v[6:7], 0, s[0:1]
	v_lshlrev_b32_e32 v0, 11, v0
	s_waitcnt lgkmcnt(6)
	v_cvt_pk_bf16_f32 v30, v36, v34
	s_waitcnt lgkmcnt(4)
	v_cvt_pk_bf16_f32 v31, v38, v40
	s_waitcnt lgkmcnt(2)
	v_cvt_pk_bf16_f32 v32, v42, v44
	s_waitcnt lgkmcnt(0)
	v_cvt_pk_bf16_f32 v33, v60, v62
	v_lshl_add_u64 v[66:67], v[64:65], 0, v[0:1]
	global_store_dwordx4 v[66:67], v[30:33], off
	v_or_b32_e32 v0, s7, v47
	v_lshlrev_b32_e32 v0, 11, v0
	v_cvt_pk_bf16_f32 v30, v37, v35
	v_cvt_pk_bf16_f32 v31, v39, v41
	v_cvt_pk_bf16_f32 v32, v43, v45
	v_cvt_pk_bf16_f32 v33, v61, v63
	ds_read2_b32 v[36:37], v46 offset0:49 offset1:57
	ds_read2_b32 v[38:39], v46 offset0:16 offset1:24
	ds_read2_b32 v[40:41], v46 offset0:82 offset1:90
	ds_read2_b32 v[42:43], v46 offset0:115 offset1:123
	ds_read2_b32 v[44:45], v46 offset0:148 offset1:156
	ds_read2_b32 v[60:61], v46 offset0:181 offset1:189
	ds_read2_b32 v[62:63], v46 offset0:214 offset1:222
	ds_read2_b32 v[66:67], v46 offset0:247 offset1:255
	v_lshl_add_u64 v[34:35], v[64:65], 0, v[0:1]
	v_or_b32_e32 v0, s7, v48
	v_lshlrev_b32_e32 v0, 11, v0
	global_store_dwordx4 v[34:35], v[30:33], off
	v_lshl_add_u64 v[34:35], v[64:65], 0, v[0:1]
	v_or_b32_e32 v0, s7, v49
	s_waitcnt lgkmcnt(6)
	v_cvt_pk_bf16_f32 v30, v38, v36
	s_waitcnt lgkmcnt(4)
	v_cvt_pk_bf16_f32 v31, v40, v42
	s_waitcnt lgkmcnt(2)
	v_cvt_pk_bf16_f32 v32, v44, v60
	s_waitcnt lgkmcnt(0)
	v_cvt_pk_bf16_f32 v33, v62, v66
	v_lshlrev_b32_e32 v0, 11, v0
	global_store_dwordx4 v[34:35], v[30:33], off
	v_lshl_add_u64 v[34:35], v[64:65], 0, v[0:1]
	s_nop 0
	v_cvt_pk_bf16_f32 v30, v39, v37
	v_cvt_pk_bf16_f32 v31, v41, v43
	v_cvt_pk_bf16_f32 v32, v45, v61
	v_cvt_pk_bf16_f32 v33, v63, v67
	global_store_dwordx4 v[34:35], v[30:33], off
	s_waitcnt lgkmcnt(0)

.LBB0_40:
	v_lshl_add_u64 v[60:61], v[44:45], 0, s[4:5]
	v_lshl_add_u64 v[62:63], v[42:43], 0, s[4:5]
	v_lshl_add_u64 v[64:65], v[40:41], 0, s[4:5]
	v_lshl_add_u64 v[66:67], v[38:39], 0, s[4:5]
	v_lshl_add_u64 v[68:69], v[36:37], 0, s[4:5]
	v_lshl_add_u64 v[70:71], v[34:35], 0, s[4:5]
	v_lshl_add_u64 v[72:73], v[32:33], 0, s[4:5]
	v_lshl_add_u64 v[74:75], v[30:31], 0, s[4:5]
	global_load_dword v128, v[60:61], off nt
	s_nop 0
	global_load_dword v129, v[62:63], off nt
	global_load_dword v130, v[64:65], off nt
	s_nop 0
	global_load_dword v131, v[66:67], off nt
	global_load_dword v132, v[68:69], off nt
	global_load_dword v133, v[70:71], off nt
	global_load_dword v134, v[72:73], off nt
	s_nop 0
	global_load_dword v135, v[74:75], off nt
	s_add_u32 s4, s4, 0x10000
	s_addc_u32 s5, s5, 0
	v_lshl_add_u64 v[60:61], v[44:45], 0, s[4:5]
	v_lshl_add_u64 v[62:63], v[42:43], 0, s[4:5]
	v_lshl_add_u64 v[64:65], v[40:41], 0, s[4:5]
	v_lshl_add_u64 v[66:67], v[38:39], 0, s[4:5]
	v_lshl_add_u64 v[68:69], v[36:37], 0, s[4:5]
	v_lshl_add_u64 v[70:71], v[34:35], 0, s[4:5]
	v_lshl_add_u64 v[72:73], v[32:33], 0, s[4:5]
	v_lshl_add_u64 v[74:75], v[30:31], 0, s[4:5]
	global_load_dword v136, v[60:61], off nt
	s_nop 0
	global_load_dword v137, v[62:63], off nt
	global_load_dword v138, v[64:65], off nt
	s_nop 0
	global_load_dword v139, v[66:67], off nt
	global_load_dword v140, v[68:69], off nt
	global_load_dword v141, v[70:71], off nt
	global_load_dword v142, v[72:73], off nt
	s_nop 0
	global_load_dword v143, v[74:75], off nt
	s_add_u32 s4, s4, 0x10000
	s_addc_u32 s5, s5, 0
	v_lshl_add_u64 v[60:61], v[44:45], 0, s[4:5]
	v_lshl_add_u64 v[62:63], v[42:43], 0, s[4:5]
	v_lshl_add_u64 v[64:65], v[40:41], 0, s[4:5]
	v_lshl_add_u64 v[66:67], v[38:39], 0, s[4:5]
	v_lshl_add_u64 v[68:69], v[36:37], 0, s[4:5]
	v_lshl_add_u64 v[70:71], v[34:35], 0, s[4:5]
	v_lshl_add_u64 v[72:73], v[32:33], 0, s[4:5]
	v_lshl_add_u64 v[74:75], v[30:31], 0, s[4:5]
	global_load_dword v144, v[60:61], off nt
	s_nop 0
	global_load_dword v145, v[62:63], off nt
	global_load_dword v146, v[64:65], off nt
	s_nop 0
	global_load_dword v147, v[66:67], off nt
	global_load_dword v148, v[68:69], off nt
	global_load_dword v149, v[70:71], off nt
	global_load_dword v150, v[72:73], off nt
	s_nop 0
	global_load_dword v151, v[74:75], off nt
	s_add_u32 s4, s4, 0x10000
	s_addc_u32 s5, s5, 0
	v_lshl_add_u64 v[60:61], v[44:45], 0, s[4:5]
	v_lshl_add_u64 v[62:63], v[42:43], 0, s[4:5]
	v_lshl_add_u64 v[64:65], v[40:41], 0, s[4:5]
	v_lshl_add_u64 v[66:67], v[38:39], 0, s[4:5]
	v_lshl_add_u64 v[68:69], v[36:37], 0, s[4:5]
	v_lshl_add_u64 v[70:71], v[34:35], 0, s[4:5]
	v_lshl_add_u64 v[72:73], v[32:33], 0, s[4:5]
	v_lshl_add_u64 v[74:75], v[30:31], 0, s[4:5]
	global_load_dword v152, v[60:61], off nt
	s_nop 0
	global_load_dword v153, v[62:63], off nt
	global_load_dword v154, v[64:65], off nt
	s_nop 0
	global_load_dword v155, v[66:67], off nt
	global_load_dword v156, v[68:69], off nt
	global_load_dword v157, v[70:71], off nt
	global_load_dword v158, v[72:73], off nt
	s_nop 0
	global_load_dword v159, v[74:75], off nt
	s_add_u32 s4, s4, 0x10000
	s_addc_u32 s5, s5, 0
	v_add_u32_e32 v67, 0x400, v0
	s_waitcnt vmcnt(30)
	ds_write2_b32 v0, v128, v129 offset1:66
	s_waitcnt vmcnt(28)
	ds_write2_b32 v0, v130, v131 offset0:132 offset1:198
	s_waitcnt vmcnt(26)
	ds_write2_b32 v67, v132, v133 offset0:8 offset1:74
	s_waitcnt vmcnt(24)
	ds_write2_b32 v67, v134, v135 offset0:140 offset1:206
	v_add_u32_e32 v0, 0x840, v0
	v_add_u32_e32 v67, 0x400, v0
	s_waitcnt vmcnt(22)
	ds_write2_b32 v0, v136, v137 offset1:66
	s_waitcnt vmcnt(20)
	ds_write2_b32 v0, v138, v139 offset0:132 offset1:198
	s_waitcnt vmcnt(18)
	ds_write2_b32 v67, v140, v141 offset0:8 offset1:74
	s_waitcnt vmcnt(16)
	ds_write2_b32 v67, v142, v143 offset0:140 offset1:206
	v_add_u32_e32 v0, 0x840, v0
	v_add_u32_e32 v67, 0x400, v0
	s_waitcnt vmcnt(14)
	ds_write2_b32 v0, v144, v145 offset1:66
	s_waitcnt vmcnt(12)
	ds_write2_b32 v0, v146, v147 offset0:132 offset1:198
	s_waitcnt vmcnt(10)
	ds_write2_b32 v67, v148, v149 offset0:8 offset1:74
	s_waitcnt vmcnt(8)
	ds_write2_b32 v67, v150, v151 offset0:140 offset1:206
	v_add_u32_e32 v0, 0x840, v0
	v_add_u32_e32 v67, 0x400, v0
	s_waitcnt vmcnt(6)
	ds_write2_b32 v0, v152, v153 offset1:66
	s_waitcnt vmcnt(4)
	ds_write2_b32 v0, v154, v155 offset0:132 offset1:198
	s_waitcnt vmcnt(2)
	ds_write2_b32 v67, v156, v157 offset0:8 offset1:74
	s_waitcnt vmcnt(0)
	ds_write2_b32 v67, v158, v159 offset0:140 offset1:206
	v_add_u32_e32 v0, 0x840, v0
	s_waitcnt lgkmcnt(0)
	s_lshl_b32 s0, s19, 1
	ds_read2_b32 v[34:35], v46 offset0:33 offset1:41
	ds_read2_b32 v[36:37], v46 offset1:8
	ds_read2_b32 v[38:39], v46 offset0:66 offset1:74
	ds_read2_b32 v[40:41], v46 offset0:99 offset1:107
	ds_read2_b32 v[42:43], v46 offset0:132 offset1:140
	ds_read2_b32 v[44:45], v46 offset0:165 offset1:173
	ds_read2_b32 v[60:61], v46 offset0:198 offset1:206
	ds_read2_b32 v[62:63], v46 offset0:231 offset1:239
	s_add_i32 s0, s0, 0x7fffcc00
	s_lshl_b32 s4, s19, 5
	s_and_b32 s0, s0, 0x7fffffc0
	s_and_b32 s4, s4, 0x3e0
	s_lshl_b32 s0, s0, 1
	v_or_b32_e32 v0, s4, v3
	v_lshl_add_u64 v[64:65], v[8:9], 0, s[0:1]
	v_lshlrev_b32_e32 v0, 11, v0
	s_waitcnt lgkmcnt(6)
	v_cvt_pk_bf16_f32 v30, v36, v34
	s_waitcnt lgkmcnt(4)
	v_cvt_pk_bf16_f32 v31, v38, v40
	s_waitcnt lgkmcnt(2)
	v_cvt_pk_bf16_f32 v32, v42, v44
	s_waitcnt lgkmcnt(0)
	v_cvt_pk_bf16_f32 v33, v60, v62
	v_lshl_add_u64 v[66:67], v[64:65], 0, v[0:1]
	global_store_dwordx4 v[66:67], v[30:33], off
	v_or_b32_e32 v0, s4, v47
	v_lshlrev_b32_e32 v0, 11, v0
	v_cvt_pk_bf16_f32 v30, v37, v35
	v_cvt_pk_bf16_f32 v31, v39, v41
	v_cvt_pk_bf16_f32 v32, v43, v45
	v_cvt_pk_bf16_f32 v33, v61, v63
	ds_read2_b32 v[36:37], v46 offset0:49 offset1:57
	ds_read2_b32 v[38:39], v46 offset0:16 offset1:24
	ds_read2_b32 v[40:41], v46 offset0:82 offset1:90
	ds_read2_b32 v[42:43], v46 offset0:115 offset1:123
	ds_read2_b32 v[44:45], v46 offset0:148 offset1:156
	ds_read2_b32 v[60:61], v46 offset0:181 offset1:189
	ds_read2_b32 v[62:63], v46 offset0:214 offset1:222
	ds_read2_b32 v[66:67], v46 offset0:247 offset1:255
	v_lshl_add_u64 v[34:35], v[64:65], 0, v[0:1]
	v_or_b32_e32 v0, s4, v48
	v_lshlrev_b32_e32 v0, 11, v0
	global_store_dwordx4 v[34:35], v[30:33], off
	v_lshl_add_u64 v[34:35], v[64:65], 0, v[0:1]
	v_or_b32_e32 v0, s4, v49
	s_waitcnt lgkmcnt(6)
	v_cvt_pk_bf16_f32 v30, v38, v36
	s_waitcnt lgkmcnt(4)
	v_cvt_pk_bf16_f32 v31, v40, v42
	s_waitcnt lgkmcnt(2)
	v_cvt_pk_bf16_f32 v32, v44, v60
	s_waitcnt lgkmcnt(0)
	v_cvt_pk_bf16_f32 v33, v62, v66
	v_lshlrev_b32_e32 v0, 11, v0
	global_store_dwordx4 v[34:35], v[30:33], off
	v_lshl_add_u64 v[34:35], v[64:65], 0, v[0:1]
	s_nop 0
	v_cvt_pk_bf16_f32 v30, v39, v37
	v_cvt_pk_bf16_f32 v31, v41, v43
	v_cvt_pk_bf16_f32 v32, v45, v61
	v_cvt_pk_bf16_f32 v33, v63, v67
	global_store_dwordx4 v[34:35], v[30:33], off
	s_waitcnt lgkmcnt(0)

.LBB0_45:
	v_lshl_add_u64 v[60:61], v[44:45], 0, s[4:5]
	v_lshl_add_u64 v[62:63], v[42:43], 0, s[4:5]
	v_lshl_add_u64 v[64:65], v[40:41], 0, s[4:5]
	v_lshl_add_u64 v[66:67], v[38:39], 0, s[4:5]
	v_lshl_add_u64 v[68:69], v[36:37], 0, s[4:5]
	v_lshl_add_u64 v[70:71], v[34:35], 0, s[4:5]
	v_lshl_add_u64 v[72:73], v[32:33], 0, s[4:5]
	v_lshl_add_u64 v[74:75], v[30:31], 0, s[4:5]
	global_load_dword v128, v[60:61], off nt
	s_nop 0
	global_load_dword v129, v[62:63], off nt
	global_load_dword v130, v[64:65], off nt
	s_nop 0
	global_load_dword v131, v[66:67], off nt
	global_load_dword v132, v[68:69], off nt
	global_load_dword v133, v[70:71], off nt
	global_load_dword v134, v[72:73], off nt
	s_nop 0
	global_load_dword v135, v[74:75], off nt
	s_add_u32 s4, s4, 0x10000
	s_addc_u32 s5, s5, 0
	v_lshl_add_u64 v[60:61], v[44:45], 0, s[4:5]
	v_lshl_add_u64 v[62:63], v[42:43], 0, s[4:5]
	v_lshl_add_u64 v[64:65], v[40:41], 0, s[4:5]
	v_lshl_add_u64 v[66:67], v[38:39], 0, s[4:5]
	v_lshl_add_u64 v[68:69], v[36:37], 0, s[4:5]
	v_lshl_add_u64 v[70:71], v[34:35], 0, s[4:5]
	v_lshl_add_u64 v[72:73], v[32:33], 0, s[4:5]
	v_lshl_add_u64 v[74:75], v[30:31], 0, s[4:5]
	global_load_dword v136, v[60:61], off nt
	s_nop 0
	global_load_dword v137, v[62:63], off nt
	global_load_dword v138, v[64:65], off nt
	s_nop 0
	global_load_dword v139, v[66:67], off nt
	global_load_dword v140, v[68:69], off nt
	global_load_dword v141, v[70:71], off nt
	global_load_dword v142, v[72:73], off nt
	s_nop 0
	global_load_dword v143, v[74:75], off nt
	s_add_u32 s4, s4, 0x10000
	s_addc_u32 s5, s5, 0
	v_lshl_add_u64 v[60:61], v[44:45], 0, s[4:5]
	v_lshl_add_u64 v[62:63], v[42:43], 0, s[4:5]
	v_lshl_add_u64 v[64:65], v[40:41], 0, s[4:5]
	v_lshl_add_u64 v[66:67], v[38:39], 0, s[4:5]
	v_lshl_add_u64 v[68:69], v[36:37], 0, s[4:5]
	v_lshl_add_u64 v[70:71], v[34:35], 0, s[4:5]
	v_lshl_add_u64 v[72:73], v[32:33], 0, s[4:5]
	v_lshl_add_u64 v[74:75], v[30:31], 0, s[4:5]
	global_load_dword v144, v[60:61], off nt
	s_nop 0
	global_load_dword v145, v[62:63], off nt
	global_load_dword v146, v[64:65], off nt
	s_nop 0
	global_load_dword v147, v[66:67], off nt
	global_load_dword v148, v[68:69], off nt
	global_load_dword v149, v[70:71], off nt
	global_load_dword v150, v[72:73], off nt
	s_nop 0
	global_load_dword v151, v[74:75], off nt
	s_add_u32 s4, s4, 0x10000
	s_addc_u32 s5, s5, 0
	v_lshl_add_u64 v[60:61], v[44:45], 0, s[4:5]
	v_lshl_add_u64 v[62:63], v[42:43], 0, s[4:5]
	v_lshl_add_u64 v[64:65], v[40:41], 0, s[4:5]
	v_lshl_add_u64 v[66:67], v[38:39], 0, s[4:5]
	v_lshl_add_u64 v[68:69], v[36:37], 0, s[4:5]
	v_lshl_add_u64 v[70:71], v[34:35], 0, s[4:5]
	v_lshl_add_u64 v[72:73], v[32:33], 0, s[4:5]
	v_lshl_add_u64 v[74:75], v[30:31], 0, s[4:5]
	global_load_dword v152, v[60:61], off nt
	s_nop 0
	global_load_dword v153, v[62:63], off nt
	global_load_dword v154, v[64:65], off nt
	s_nop 0
	global_load_dword v155, v[66:67], off nt
	global_load_dword v156, v[68:69], off nt
	global_load_dword v157, v[70:71], off nt
	global_load_dword v158, v[72:73], off nt
	s_nop 0
	global_load_dword v159, v[74:75], off nt
	s_add_u32 s4, s4, 0x10000
	s_addc_u32 s5, s5, 0
	v_add_u32_e32 v67, 0x400, v0
	s_waitcnt vmcnt(30)
	ds_write2_b32 v0, v128, v129 offset1:66
	s_waitcnt vmcnt(28)
	ds_write2_b32 v0, v130, v131 offset0:132 offset1:198
	s_waitcnt vmcnt(26)
	ds_write2_b32 v67, v132, v133 offset0:8 offset1:74
	s_waitcnt vmcnt(24)
	ds_write2_b32 v67, v134, v135 offset0:140 offset1:206
	v_add_u32_e32 v0, 0x840, v0
	v_add_u32_e32 v67, 0x400, v0
	s_waitcnt vmcnt(22)
	ds_write2_b32 v0, v136, v137 offset1:66
	s_waitcnt vmcnt(20)
	ds_write2_b32 v0, v138, v139 offset0:132 offset1:198
	s_waitcnt vmcnt(18)
	ds_write2_b32 v67, v140, v141 offset0:8 offset1:74
	s_waitcnt vmcnt(16)
	ds_write2_b32 v67, v142, v143 offset0:140 offset1:206
	v_add_u32_e32 v0, 0x840, v0
	v_add_u32_e32 v67, 0x400, v0
	s_waitcnt vmcnt(14)
	ds_write2_b32 v0, v144, v145 offset1:66
	s_waitcnt vmcnt(12)
	ds_write2_b32 v0, v146, v147 offset0:132 offset1:198
	s_waitcnt vmcnt(10)
	ds_write2_b32 v67, v148, v149 offset0:8 offset1:74
	s_waitcnt vmcnt(8)
	ds_write2_b32 v67, v150, v151 offset0:140 offset1:206
	v_add_u32_e32 v0, 0x840, v0
	v_add_u32_e32 v67, 0x400, v0
	s_waitcnt vmcnt(6)
	ds_write2_b32 v0, v152, v153 offset1:66
	s_waitcnt vmcnt(4)
	ds_write2_b32 v0, v154, v155 offset0:132 offset1:198
	s_waitcnt vmcnt(2)
	ds_write2_b32 v67, v156, v157 offset0:8 offset1:74
	s_waitcnt vmcnt(0)
	ds_write2_b32 v67, v158, v159 offset0:140 offset1:206
	v_add_u32_e32 v0, 0x840, v0
	s_waitcnt lgkmcnt(0)
	s_lshl_b32 s0, s19, 1
	ds_read2_b32 v[34:35], v46 offset0:33 offset1:41
	ds_read2_b32 v[36:37], v46 offset1:8
	ds_read2_b32 v[38:39], v46 offset0:66 offset1:74
	ds_read2_b32 v[40:41], v46 offset0:99 offset1:107
	ds_read2_b32 v[42:43], v46 offset0:132 offset1:140
	ds_read2_b32 v[44:45], v46 offset0:165 offset1:173
	ds_read2_b32 v[60:61], v46 offset0:198 offset1:206
	ds_read2_b32 v[62:63], v46 offset0:231 offset1:239
	s_add_i32 s0, s0, 0x7fffd000
	s_lshl_b32 s4, s19, 5
	s_and_b32 s0, s0, 0x7fffffc0
	s_and_b32 s4, s4, 0x3e0
	s_lshl_b32 s0, s0, 1
	v_or_b32_e32 v0, s4, v3
	v_lshl_add_u64 v[64:65], v[10:11], 0, s[0:1]
	v_lshlrev_b32_e32 v0, 11, v0
	s_waitcnt lgkmcnt(6)
	v_cvt_pk_bf16_f32 v30, v36, v34
	s_waitcnt lgkmcnt(4)
	v_cvt_pk_bf16_f32 v31, v38, v40
	s_waitcnt lgkmcnt(2)
	v_cvt_pk_bf16_f32 v32, v42, v44
	s_waitcnt lgkmcnt(0)
	v_cvt_pk_bf16_f32 v33, v60, v62
	v_lshl_add_u64 v[66:67], v[64:65], 0, v[0:1]
	global_store_dwordx4 v[66:67], v[30:33], off
	v_or_b32_e32 v0, s4, v47
	v_lshlrev_b32_e32 v0, 11, v0
	v_cvt_pk_bf16_f32 v30, v37, v35
	v_cvt_pk_bf16_f32 v31, v39, v41
	v_cvt_pk_bf16_f32 v32, v43, v45
	v_cvt_pk_bf16_f32 v33, v61, v63
	ds_read2_b32 v[36:37], v46 offset0:49 offset1:57
	ds_read2_b32 v[38:39], v46 offset0:16 offset1:24
	ds_read2_b32 v[40:41], v46 offset0:82 offset1:90
	ds_read2_b32 v[42:43], v46 offset0:115 offset1:123
	ds_read2_b32 v[44:45], v46 offset0:148 offset1:156
	ds_read2_b32 v[60:61], v46 offset0:181 offset1:189
	ds_read2_b32 v[62:63], v46 offset0:214 offset1:222
	ds_read2_b32 v[66:67], v46 offset0:247 offset1:255
	v_lshl_add_u64 v[34:35], v[64:65], 0, v[0:1]
	v_or_b32_e32 v0, s4, v48
	v_lshlrev_b32_e32 v0, 11, v0
	global_store_dwordx4 v[34:35], v[30:33], off
	v_lshl_add_u64 v[34:35], v[64:65], 0, v[0:1]
	v_or_b32_e32 v0, s4, v49
	s_waitcnt lgkmcnt(6)
	v_cvt_pk_bf16_f32 v30, v38, v36
	s_waitcnt lgkmcnt(4)
	v_cvt_pk_bf16_f32 v31, v40, v42
	s_waitcnt lgkmcnt(2)
	v_cvt_pk_bf16_f32 v32, v44, v60
	s_waitcnt lgkmcnt(0)
	v_cvt_pk_bf16_f32 v33, v62, v66
	v_lshlrev_b32_e32 v0, 11, v0
	global_store_dwordx4 v[34:35], v[30:33], off
	v_lshl_add_u64 v[34:35], v[64:65], 0, v[0:1]
	s_nop 0
	v_cvt_pk_bf16_f32 v30, v39, v37
	v_cvt_pk_bf16_f32 v31, v41, v43
	v_cvt_pk_bf16_f32 v32, v45, v61
	v_cvt_pk_bf16_f32 v33, v63, v67
	global_store_dwordx4 v[34:35], v[30:33], off
	s_waitcnt lgkmcnt(0)

.LBB0_50:
	v_lshl_add_u64 v[60:61], v[44:45], 0, s[4:5]
	v_lshl_add_u64 v[62:63], v[42:43], 0, s[4:5]
	v_lshl_add_u64 v[64:65], v[40:41], 0, s[4:5]
	v_lshl_add_u64 v[66:67], v[38:39], 0, s[4:5]
	v_lshl_add_u64 v[68:69], v[36:37], 0, s[4:5]
	v_lshl_add_u64 v[70:71], v[34:35], 0, s[4:5]
	v_lshl_add_u64 v[72:73], v[32:33], 0, s[4:5]
	v_lshl_add_u64 v[74:75], v[30:31], 0, s[4:5]
	global_load_dword v128, v[60:61], off nt
	s_nop 0
	global_load_dword v129, v[62:63], off nt
	global_load_dword v130, v[64:65], off nt
	s_nop 0
	global_load_dword v131, v[66:67], off nt
	global_load_dword v132, v[68:69], off nt
	global_load_dword v133, v[70:71], off nt
	global_load_dword v134, v[72:73], off nt
	s_nop 0
	global_load_dword v135, v[74:75], off nt
	s_add_u32 s4, s4, 0x10000
	s_addc_u32 s5, s5, 0
	v_lshl_add_u64 v[60:61], v[44:45], 0, s[4:5]
	v_lshl_add_u64 v[62:63], v[42:43], 0, s[4:5]
	v_lshl_add_u64 v[64:65], v[40:41], 0, s[4:5]
	v_lshl_add_u64 v[66:67], v[38:39], 0, s[4:5]
	v_lshl_add_u64 v[68:69], v[36:37], 0, s[4:5]
	v_lshl_add_u64 v[70:71], v[34:35], 0, s[4:5]
	v_lshl_add_u64 v[72:73], v[32:33], 0, s[4:5]
	v_lshl_add_u64 v[74:75], v[30:31], 0, s[4:5]
	global_load_dword v136, v[60:61], off nt
	s_nop 0
	global_load_dword v137, v[62:63], off nt
	global_load_dword v138, v[64:65], off nt
	s_nop 0
	global_load_dword v139, v[66:67], off nt
	global_load_dword v140, v[68:69], off nt
	global_load_dword v141, v[70:71], off nt
	global_load_dword v142, v[72:73], off nt
	s_nop 0
	global_load_dword v143, v[74:75], off nt
	s_add_u32 s4, s4, 0x10000
	s_addc_u32 s5, s5, 0
	v_lshl_add_u64 v[60:61], v[44:45], 0, s[4:5]
	v_lshl_add_u64 v[62:63], v[42:43], 0, s[4:5]
	v_lshl_add_u64 v[64:65], v[40:41], 0, s[4:5]
	v_lshl_add_u64 v[66:67], v[38:39], 0, s[4:5]
	v_lshl_add_u64 v[68:69], v[36:37], 0, s[4:5]
	v_lshl_add_u64 v[70:71], v[34:35], 0, s[4:5]
	v_lshl_add_u64 v[72:73], v[32:33], 0, s[4:5]
	v_lshl_add_u64 v[74:75], v[30:31], 0, s[4:5]
	global_load_dword v144, v[60:61], off nt
	s_nop 0
	global_load_dword v145, v[62:63], off nt
	global_load_dword v146, v[64:65], off nt
	s_nop 0
	global_load_dword v147, v[66:67], off nt
	global_load_dword v148, v[68:69], off nt
	global_load_dword v149, v[70:71], off nt
	global_load_dword v150, v[72:73], off nt
	s_nop 0
	global_load_dword v151, v[74:75], off nt
	s_add_u32 s4, s4, 0x10000
	s_addc_u32 s5, s5, 0
	v_lshl_add_u64 v[60:61], v[44:45], 0, s[4:5]
	v_lshl_add_u64 v[62:63], v[42:43], 0, s[4:5]
	v_lshl_add_u64 v[64:65], v[40:41], 0, s[4:5]
	v_lshl_add_u64 v[66:67], v[38:39], 0, s[4:5]
	v_lshl_add_u64 v[68:69], v[36:37], 0, s[4:5]
	v_lshl_add_u64 v[70:71], v[34:35], 0, s[4:5]
	v_lshl_add_u64 v[72:73], v[32:33], 0, s[4:5]
	v_lshl_add_u64 v[74:75], v[30:31], 0, s[4:5]
	global_load_dword v152, v[60:61], off nt
	s_nop 0
	global_load_dword v153, v[62:63], off nt
	global_load_dword v154, v[64:65], off nt
	s_nop 0
	global_load_dword v155, v[66:67], off nt
	global_load_dword v156, v[68:69], off nt
	global_load_dword v157, v[70:71], off nt
	global_load_dword v158, v[72:73], off nt
	s_nop 0
	global_load_dword v159, v[74:75], off nt
	s_add_u32 s4, s4, 0x10000
	s_addc_u32 s5, s5, 0
	v_add_u32_e32 v67, 0x400, v0
	s_waitcnt vmcnt(30)
	ds_write2_b32 v0, v128, v129 offset1:66
	s_waitcnt vmcnt(28)
	ds_write2_b32 v0, v130, v131 offset0:132 offset1:198
	s_waitcnt vmcnt(26)
	ds_write2_b32 v67, v132, v133 offset0:8 offset1:74
	s_waitcnt vmcnt(24)
	ds_write2_b32 v67, v134, v135 offset0:140 offset1:206
	v_add_u32_e32 v0, 0x840, v0
	v_add_u32_e32 v67, 0x400, v0
	s_waitcnt vmcnt(22)
	ds_write2_b32 v0, v136, v137 offset1:66
	s_waitcnt vmcnt(20)
	ds_write2_b32 v0, v138, v139 offset0:132 offset1:198
	s_waitcnt vmcnt(18)
	ds_write2_b32 v67, v140, v141 offset0:8 offset1:74
	s_waitcnt vmcnt(16)
	ds_write2_b32 v67, v142, v143 offset0:140 offset1:206
	v_add_u32_e32 v0, 0x840, v0
	v_add_u32_e32 v67, 0x400, v0
	s_waitcnt vmcnt(14)
	ds_write2_b32 v0, v144, v145 offset1:66
	s_waitcnt vmcnt(12)
	ds_write2_b32 v0, v146, v147 offset0:132 offset1:198
	s_waitcnt vmcnt(10)
	ds_write2_b32 v67, v148, v149 offset0:8 offset1:74
	s_waitcnt vmcnt(8)
	ds_write2_b32 v67, v150, v151 offset0:140 offset1:206
	v_add_u32_e32 v0, 0x840, v0
	v_add_u32_e32 v67, 0x400, v0
	s_waitcnt vmcnt(6)
	ds_write2_b32 v0, v152, v153 offset1:66
	s_waitcnt vmcnt(4)
	ds_write2_b32 v0, v154, v155 offset0:132 offset1:198
	s_waitcnt vmcnt(2)
	ds_write2_b32 v67, v156, v157 offset0:8 offset1:74
	s_waitcnt vmcnt(0)
	ds_write2_b32 v67, v158, v159 offset0:140 offset1:206
	v_add_u32_e32 v0, 0x840, v0
	s_waitcnt lgkmcnt(0)
	s_lshl_b32 s0, s19, 1
	ds_read2_b32 v[34:35], v46 offset0:33 offset1:41
	ds_read2_b32 v[36:37], v46 offset1:8
	ds_read2_b32 v[38:39], v46 offset0:66 offset1:74
	ds_read2_b32 v[40:41], v46 offset0:99 offset1:107
	ds_read2_b32 v[42:43], v46 offset0:132 offset1:140
	ds_read2_b32 v[44:45], v46 offset0:165 offset1:173
	ds_read2_b32 v[60:61], v46 offset0:198 offset1:206
	ds_read2_b32 v[62:63], v46 offset0:231 offset1:239
	s_add_i32 s0, s0, 0x7fffd200
	s_lshl_b32 s4, s19, 5
	s_and_b32 s0, s0, 0x7fffffc0
	s_and_b32 s4, s4, 0x3e0
	s_lshl_b32 s0, s0, 1
	v_or_b32_e32 v0, s4, v3
	v_lshl_add_u64 v[64:65], v[12:13], 0, s[0:1]
	v_lshlrev_b32_e32 v0, 10, v0
	s_waitcnt lgkmcnt(6)
	v_cvt_pk_bf16_f32 v30, v36, v34
	s_waitcnt lgkmcnt(4)
	v_cvt_pk_bf16_f32 v31, v38, v40
	s_waitcnt lgkmcnt(2)
	v_cvt_pk_bf16_f32 v32, v42, v44
	s_waitcnt lgkmcnt(0)
	v_cvt_pk_bf16_f32 v33, v60, v62
	v_lshl_add_u64 v[66:67], v[64:65], 0, v[0:1]
	global_store_dwordx4 v[66:67], v[30:33], off
	v_or_b32_e32 v0, s4, v47
	v_lshlrev_b32_e32 v0, 10, v0
	v_cvt_pk_bf16_f32 v30, v37, v35
	v_cvt_pk_bf16_f32 v31, v39, v41
	v_cvt_pk_bf16_f32 v32, v43, v45
	v_cvt_pk_bf16_f32 v33, v61, v63
	ds_read2_b32 v[36:37], v46 offset0:49 offset1:57
	ds_read2_b32 v[38:39], v46 offset0:16 offset1:24
	ds_read2_b32 v[40:41], v46 offset0:82 offset1:90
	ds_read2_b32 v[42:43], v46 offset0:115 offset1:123
	ds_read2_b32 v[44:45], v46 offset0:148 offset1:156
	ds_read2_b32 v[60:61], v46 offset0:181 offset1:189
	ds_read2_b32 v[62:63], v46 offset0:214 offset1:222
	ds_read2_b32 v[66:67], v46 offset0:247 offset1:255
	v_lshl_add_u64 v[34:35], v[64:65], 0, v[0:1]
	v_or_b32_e32 v0, s4, v48
	v_lshlrev_b32_e32 v0, 10, v0
	global_store_dwordx4 v[34:35], v[30:33], off
	v_lshl_add_u64 v[34:35], v[64:65], 0, v[0:1]
	v_or_b32_e32 v0, s4, v49
	s_waitcnt lgkmcnt(6)
	v_cvt_pk_bf16_f32 v30, v38, v36
	s_waitcnt lgkmcnt(4)
	v_cvt_pk_bf16_f32 v31, v40, v42
	s_waitcnt lgkmcnt(2)
	v_cvt_pk_bf16_f32 v32, v44, v60
	s_waitcnt lgkmcnt(0)
	v_cvt_pk_bf16_f32 v33, v62, v66
	v_lshlrev_b32_e32 v0, 10, v0
	global_store_dwordx4 v[34:35], v[30:33], off
	v_lshl_add_u64 v[34:35], v[64:65], 0, v[0:1]
	s_nop 0
	v_cvt_pk_bf16_f32 v30, v39, v37
	v_cvt_pk_bf16_f32 v31, v41, v43
	v_cvt_pk_bf16_f32 v32, v45, v61
	v_cvt_pk_bf16_f32 v33, v63, v67
	global_store_dwordx4 v[34:35], v[30:33], off
	s_waitcnt lgkmcnt(0)

.LBB0_55:
	v_lshl_add_u64 v[60:61], v[44:45], 0, s[8:9]
	v_lshl_add_u64 v[62:63], v[42:43], 0, s[8:9]
	v_lshl_add_u64 v[64:65], v[40:41], 0, s[8:9]
	v_lshl_add_u64 v[66:67], v[38:39], 0, s[8:9]
	v_lshl_add_u64 v[68:69], v[36:37], 0, s[8:9]
	v_lshl_add_u64 v[70:71], v[34:35], 0, s[8:9]
	v_lshl_add_u64 v[72:73], v[32:33], 0, s[8:9]
	v_lshl_add_u64 v[74:75], v[30:31], 0, s[8:9]
	global_load_dword v128, v[60:61], off nt
	s_nop 0
	global_load_dword v129, v[62:63], off nt
	global_load_dword v130, v[64:65], off nt
	s_nop 0
	global_load_dword v131, v[66:67], off nt
	global_load_dword v132, v[68:69], off nt
	global_load_dword v133, v[70:71], off nt
	global_load_dword v134, v[72:73], off nt
	s_nop 0
	global_load_dword v135, v[74:75], off nt
	s_add_u32 s8, s8, 0xb8000
	s_addc_u32 s9, s9, 0
	v_lshl_add_u64 v[60:61], v[44:45], 0, s[8:9]
	v_lshl_add_u64 v[62:63], v[42:43], 0, s[8:9]
	v_lshl_add_u64 v[64:65], v[40:41], 0, s[8:9]
	v_lshl_add_u64 v[66:67], v[38:39], 0, s[8:9]
	v_lshl_add_u64 v[68:69], v[36:37], 0, s[8:9]
	v_lshl_add_u64 v[70:71], v[34:35], 0, s[8:9]
	v_lshl_add_u64 v[72:73], v[32:33], 0, s[8:9]
	v_lshl_add_u64 v[74:75], v[30:31], 0, s[8:9]
	global_load_dword v136, v[60:61], off nt
	s_nop 0
	global_load_dword v137, v[62:63], off nt
	global_load_dword v138, v[64:65], off nt
	s_nop 0
	global_load_dword v139, v[66:67], off nt
	global_load_dword v140, v[68:69], off nt
	global_load_dword v141, v[70:71], off nt
	global_load_dword v142, v[72:73], off nt
	s_nop 0
	global_load_dword v143, v[74:75], off nt
	s_add_u32 s8, s8, 0xb8000
	s_addc_u32 s9, s9, 0
	v_lshl_add_u64 v[60:61], v[44:45], 0, s[8:9]
	v_lshl_add_u64 v[62:63], v[42:43], 0, s[8:9]
	v_lshl_add_u64 v[64:65], v[40:41], 0, s[8:9]
	v_lshl_add_u64 v[66:67], v[38:39], 0, s[8:9]
	v_lshl_add_u64 v[68:69], v[36:37], 0, s[8:9]
	v_lshl_add_u64 v[70:71], v[34:35], 0, s[8:9]
	v_lshl_add_u64 v[72:73], v[32:33], 0, s[8:9]
	v_lshl_add_u64 v[74:75], v[30:31], 0, s[8:9]
	global_load_dword v144, v[60:61], off nt
	s_nop 0
	global_load_dword v145, v[62:63], off nt
	global_load_dword v146, v[64:65], off nt
	s_nop 0
	global_load_dword v147, v[66:67], off nt
	global_load_dword v148, v[68:69], off nt
	global_load_dword v149, v[70:71], off nt
	global_load_dword v150, v[72:73], off nt
	s_nop 0
	global_load_dword v151, v[74:75], off nt
	s_add_u32 s8, s8, 0xb8000
	s_addc_u32 s9, s9, 0
	v_lshl_add_u64 v[60:61], v[44:45], 0, s[8:9]
	v_lshl_add_u64 v[62:63], v[42:43], 0, s[8:9]
	v_lshl_add_u64 v[64:65], v[40:41], 0, s[8:9]
	v_lshl_add_u64 v[66:67], v[38:39], 0, s[8:9]
	v_lshl_add_u64 v[68:69], v[36:37], 0, s[8:9]
	v_lshl_add_u64 v[70:71], v[34:35], 0, s[8:9]
	v_lshl_add_u64 v[72:73], v[32:33], 0, s[8:9]
	v_lshl_add_u64 v[74:75], v[30:31], 0, s[8:9]
	global_load_dword v152, v[60:61], off nt
	s_nop 0
	global_load_dword v153, v[62:63], off nt
	global_load_dword v154, v[64:65], off nt
	s_nop 0
	global_load_dword v155, v[66:67], off nt
	global_load_dword v156, v[68:69], off nt
	global_load_dword v157, v[70:71], off nt
	global_load_dword v158, v[72:73], off nt
	s_nop 0
	global_load_dword v159, v[74:75], off nt
	s_add_u32 s8, s8, 0xb8000
	s_addc_u32 s9, s9, 0
	v_add_u32_e32 v67, 0x400, v0
	s_waitcnt vmcnt(30)
	ds_write2_b32 v0, v128, v129 offset1:66
	s_waitcnt vmcnt(28)
	ds_write2_b32 v0, v130, v131 offset0:132 offset1:198
	s_waitcnt vmcnt(26)
	ds_write2_b32 v67, v132, v133 offset0:8 offset1:74
	s_waitcnt vmcnt(24)
	ds_write2_b32 v67, v134, v135 offset0:140 offset1:206
	v_add_u32_e32 v0, 0x840, v0
	v_add_u32_e32 v67, 0x400, v0
	s_waitcnt vmcnt(22)
	ds_write2_b32 v0, v136, v137 offset1:66
	s_waitcnt vmcnt(20)
	ds_write2_b32 v0, v138, v139 offset0:132 offset1:198
	s_waitcnt vmcnt(18)
	ds_write2_b32 v67, v140, v141 offset0:8 offset1:74
	s_waitcnt vmcnt(16)
	ds_write2_b32 v67, v142, v143 offset0:140 offset1:206
	v_add_u32_e32 v0, 0x840, v0
	v_add_u32_e32 v67, 0x400, v0
	s_waitcnt vmcnt(14)
	ds_write2_b32 v0, v144, v145 offset1:66
	s_waitcnt vmcnt(12)
	ds_write2_b32 v0, v146, v147 offset0:132 offset1:198
	s_waitcnt vmcnt(10)
	ds_write2_b32 v67, v148, v149 offset0:8 offset1:74
	s_waitcnt vmcnt(8)
	ds_write2_b32 v67, v150, v151 offset0:140 offset1:206
	v_add_u32_e32 v0, 0x840, v0
	v_add_u32_e32 v67, 0x400, v0
	s_waitcnt vmcnt(6)
	ds_write2_b32 v0, v152, v153 offset1:66
	s_waitcnt vmcnt(4)
	ds_write2_b32 v0, v154, v155 offset0:132 offset1:198
	s_waitcnt vmcnt(2)
	ds_write2_b32 v67, v156, v157 offset0:8 offset1:74
	s_waitcnt vmcnt(0)
	ds_write2_b32 v67, v158, v159 offset0:140 offset1:206
	v_add_u32_e32 v0, 0x840, v0
	s_waitcnt lgkmcnt(0)
	ds_read2_b32 v[34:35], v46 offset0:33 offset1:41
	ds_read2_b32 v[36:37], v46 offset1:8
	ds_read2_b32 v[38:39], v46 offset0:66 offset1:74
	ds_read2_b32 v[40:41], v46 offset0:99 offset1:107
	ds_read2_b32 v[42:43], v46 offset0:132 offset1:140
	ds_read2_b32 v[44:45], v46 offset0:165 offset1:173
	ds_read2_b32 v[60:61], v46 offset0:198 offset1:206
	ds_read2_b32 v[62:63], v46 offset0:231 offset1:239
	v_or_b32_e32 v66, s4, v3
	v_ashrrev_i32_e32 v67, 31, v66
	v_lshl_add_u64 v[64:65], s[6:7], 1, v[14:15]
	v_lshlrev_b64 v[66:67], 11, v[66:67]
	s_waitcnt lgkmcnt(6)
	v_cvt_pk_bf16_f32 v30, v36, v34
	s_waitcnt lgkmcnt(4)
	v_cvt_pk_bf16_f32 v31, v38, v40
	s_waitcnt lgkmcnt(2)
	v_cvt_pk_bf16_f32 v32, v42, v44
	s_waitcnt lgkmcnt(0)
	v_cvt_pk_bf16_f32 v33, v60, v62
	v_lshl_add_u64 v[66:67], v[64:65], 0, v[66:67]
	v_or_b32_e32 v34, s4, v47
	global_store_dwordx4 v[66:67], v[30:33], off
	s_nop 1
	v_cvt_pk_bf16_f32 v30, v37, v35
	v_ashrrev_i32_e32 v35, 31, v34
	v_cvt_pk_bf16_f32 v31, v39, v41
	v_cvt_pk_bf16_f32 v32, v43, v45
	v_cvt_pk_bf16_f32 v33, v61, v63
	v_lshlrev_b64 v[34:35], 11, v[34:35]
	ds_read2_b32 v[36:37], v46 offset0:49 offset1:57
	ds_read2_b32 v[38:39], v46 offset0:16 offset1:24
	ds_read2_b32 v[40:41], v46 offset0:82 offset1:90
	ds_read2_b32 v[42:43], v46 offset0:115 offset1:123
	ds_read2_b32 v[44:45], v46 offset0:148 offset1:156
	ds_read2_b32 v[60:61], v46 offset0:181 offset1:189
	ds_read2_b32 v[62:63], v46 offset0:214 offset1:222
	ds_read2_b32 v[66:67], v46 offset0:247 offset1:255
	v_lshl_add_u64 v[34:35], v[64:65], 0, v[34:35]
	global_store_dwordx4 v[34:35], v[30:33], off
	v_or_b32_e32 v34, s4, v48
	v_ashrrev_i32_e32 v35, 31, v34
	v_lshlrev_b64 v[34:35], 11, v[34:35]
	s_waitcnt lgkmcnt(6)
	v_cvt_pk_bf16_f32 v30, v38, v36
	s_waitcnt lgkmcnt(4)
	v_cvt_pk_bf16_f32 v31, v40, v42
	s_waitcnt lgkmcnt(2)
	v_cvt_pk_bf16_f32 v32, v44, v60
	s_waitcnt lgkmcnt(0)
	v_cvt_pk_bf16_f32 v33, v62, v66
	v_lshl_add_u64 v[34:35], v[64:65], 0, v[34:35]
	global_store_dwordx4 v[34:35], v[30:33], off
	v_or_b32_e32 v34, s4, v49
	v_ashrrev_i32_e32 v35, 31, v34
	v_lshlrev_b64 v[34:35], 11, v[34:35]
	v_cvt_pk_bf16_f32 v30, v39, v37
	v_cvt_pk_bf16_f32 v31, v41, v43
	v_cvt_pk_bf16_f32 v32, v45, v61
	v_cvt_pk_bf16_f32 v33, v63, v67
	v_lshl_add_u64 v[34:35], v[64:65], 0, v[34:35]
	global_store_dwordx4 v[34:35], v[30:33], off
	s_waitcnt lgkmcnt(0)
	s_branch .LBB0_24
.LBB0_57:
	s_cmpk_gt_i32 s84, 0x3fff
	s_cbranch_scc1 .LBB0_62
	v_mbcnt_lo_u32_b32 v0, -1, 0
	v_mbcnt_hi_u32_b32 v0, -1, v0
	v_and_b32_e32 v1, 64, v0
	v_add_u32_e32 v1, 64, v1
	v_xor_b32_e32 v2, 1, v0
	v_cmp_lt_i32_e64 s[0:1], v2, v1
	s_ashr_i32 s85, s84, 31
	v_readlane_b32 s8, v246, 4
	v_cndmask_b32_e64 v2, v0, v2, s[0:1]
	v_lshlrev_b32_e32 v26, 2, v2
	v_xor_b32_e32 v2, 2, v0
	v_cmp_lt_i32_e64 s[0:1], v2, v1
	v_readlane_b32 s9, v246, 5
	v_lshlrev_b32_e32 v16, 4, v170
	v_cndmask_b32_e64 v2, v0, v2, s[0:1]
	v_lshlrev_b32_e32 v27, 2, v2
	v_xor_b32_e32 v2, 4, v0
	v_cmp_lt_i32_e64 s[0:1], v2, v1
	v_mov_b32_e32 v17, 0
	v_readlane_b32 s12, v246, 8
	v_cndmask_b32_e64 v2, v0, v2, s[0:1]
	v_lshlrev_b32_e32 v28, 2, v2
	v_xor_b32_e32 v2, 8, v0
	v_cmp_lt_i32_e64 s[0:1], v2, v1
	v_readlane_b32 s13, v246, 9
	v_readlane_b32 s14, v246, 10
	v_cndmask_b32_e64 v2, v0, v2, s[0:1]
	v_lshlrev_b32_e32 v29, 2, v2
	v_xor_b32_e32 v2, 16, v0
	v_cmp_lt_i32_e64 s[0:1], v2, v1
	v_readlane_b32 s15, v246, 11
	v_readlane_b32 s16, v246, 12
	v_cndmask_b32_e64 v2, v0, v2, s[0:1]
	v_lshlrev_b32_e32 v30, 2, v2
	v_xor_b32_e32 v2, 32, v0
	v_cmp_lt_i32_e64 s[0:1], v2, v1
	v_readlane_b32 s17, v246, 13
	v_readlane_b32 s18, v246, 14
	v_cndmask_b32_e64 v0, v0, v2, s[0:1]
	s_lshl_b64 s[0:1], s[84:85], 3
	s_add_u32 s0, s76, s0
	s_addc_u32 s1, s77, s1
	s_ashr_i32 s87, s86, 31
	s_lshl_b64 s[4:5], s[86:87], 3
	s_lshl_b64 s[6:7], s[84:85], 12
	s_add_u32 s6, s8, s6
	v_readlane_b32 s19, v246, 15
	v_readlane_b32 s20, v246, 16
	v_readlane_b32 s21, v246, 17
	v_readlane_b32 s22, v246, 18
	v_readlane_b32 s23, v246, 19
	s_addc_u32 s7, s9, s7
	v_lshl_add_u64 v[20:21], s[12:13], 0, v[16:17]
	v_lshlrev_b32_e32 v31, 2, v0
	v_lshl_add_u64 v[0:1], s[6:7], 0, v[16:17]
	s_mov_b64 s[6:7], 0xc00
	v_readlane_b32 s12, v246, 20
	v_lshl_add_u64 v[22:23], v[0:1], 0, s[6:7]
	s_lshl_b64 s[6:7], s[86:87], 12
	s_lshl_b64 s[8:9], s[84:85], 11
	v_readlane_b32 s26, v246, 34
	v_readlane_b32 s10, v246, 6
	v_readlane_b32 s11, v246, 7
	v_readlane_b32 s27, v246, 35
	s_add_u32 s8, s26, s8
	v_lshl_add_u64 v[18:19], s[10:11], 0, v[16:17]
	v_lshlrev_b32_e32 v16, 3, v170
	s_addc_u32 s9, s27, s9
	v_cmp_eq_u32_e32 vcc, 0, v170
	v_lshl_add_u64 v[24:25], s[8:9], 0, v[16:17]
	s_lshl_b64 s[8:9], s[86:87], 11
	v_mov_b32_e32 v32, 0x3727c5ac
	s_mov_b32 s12, s84
	v_readlane_b32 s13, v246, 21
	v_readlane_b32 s14, v246, 22
	v_readlane_b32 s15, v246, 23
	v_readlane_b32 s16, v246, 24
	v_readlane_b32 s17, v246, 25
	v_readlane_b32 s18, v246, 26
	v_readlane_b32 s19, v246, 27
	v_readlane_b32 s20, v246, 28
	v_readlane_b32 s21, v246, 29
	v_readlane_b32 s22, v246, 30
	v_readlane_b32 s23, v246, 31
	v_readlane_b32 s24, v246, 32
	v_readlane_b32 s25, v246, 33
	global_load_dwordx4 v[96:99], v[18:19], off
	global_load_dwordx4 v[112:115], v[20:21], off
	global_load_dwordx4 v[100:103], v[18:19], off offset:1024
	global_load_dwordx4 v[116:119], v[20:21], off offset:1024
	global_load_dwordx4 v[104:107], v[18:19], off offset:2048
	global_load_dwordx4 v[120:123], v[20:21], off offset:2048
	global_load_dwordx4 v[108:111], v[18:19], off offset:3072
	global_load_dwordx4 v[124:127], v[20:21], off offset:3072
	global_load_dwordx4 v[12:15], v[22:23], off offset:-3072 nt
	global_load_dwordx4 v[8:11], v[22:23], off offset:-2048 nt
	global_load_dwordx4 v[4:7], v[22:23], off offset:-1024 nt
	global_load_dwordx4 v[0:3], v[22:23], off nt
	s_waitcnt vmcnt(0)
.Lln_loop:
	s_add_i32 s13, s12, s86
	s_cmpk_lt_i32 s13, 0x4000
	s_cselect_b32 s14, s6, 0
	s_cselect_b32 s15, s7, 0
	v_lshl_add_u64 v[22:23], v[22:23], 0, s[14:15]
	global_load_dwordx4 v[92:95], v[22:23], off offset:-3072 nt
	global_load_dwordx4 v[88:91], v[22:23], off offset:-2048 nt
	global_load_dwordx4 v[84:87], v[22:23], off offset:-1024 nt
	global_load_dwordx4 v[80:83], v[22:23], off nt
	s_waitcnt vmcnt(9)
	v_mov_b32_e32 v34, v13
	v_mov_b32_e32 v35, v14
	v_mov_b32_e32 v36, v12
	v_mov_b32_e32 v37, v15
	v_mov_b32_e32 v38, v9
	v_mov_b32_e32 v39, v10
	v_mov_b32_e32 v40, v8
	v_mov_b32_e32 v41, v11
	v_pk_add_f32 v[34:35], v[34:35], v[36:37]
	v_pk_add_f32 v[36:37], v[38:39], v[40:41]
	v_add_f32_e32 v16, v34, v35
	v_pk_add_f32 v[34:35], v[36:37], v[36:37] op_sel:[0,1] op_sel_hi:[1,0]
	v_add_f32_e32 v42, v4, v5
	v_add_f32_e32 v44, v6, v7
	v_mov_b32_e32 v47, v0
	v_mov_b32_e32 v43, v2
	v_mov_b32_e32 v45, v3
	v_add_f32_e32 v46, 0, v16
	v_mov_b32_e32 v35, v1
	v_pk_add_f32 v[38:39], v[42:43], v[44:45]
	v_pk_add_f32 v[34:35], v[46:47], v[34:35]
	s_nop 0
	v_pk_add_f32 v[34:35], v[34:35], v[38:39]
	s_nop 0
	v_add_f32_e32 v16, v34, v35
	ds_bpermute_b32 v33, v26, v16
	s_waitcnt lgkmcnt(0)
	v_add_f32_e32 v16, v16, v33
	ds_bpermute_b32 v33, v27, v16
	s_waitcnt lgkmcnt(0)
	v_add_f32_e32 v16, v16, v33
	ds_bpermute_b32 v33, v28, v16
	s_waitcnt lgkmcnt(0)
	v_add_f32_e32 v16, v16, v33
	ds_bpermute_b32 v33, v29, v16
	s_waitcnt lgkmcnt(0)
	v_add_f32_e32 v16, v16, v33
	ds_bpermute_b32 v33, v30, v16
	s_waitcnt lgkmcnt(0)
	v_add_f32_e32 v16, v16, v33
	ds_bpermute_b32 v33, v31, v16
	s_waitcnt lgkmcnt(0)
	v_add_f32_e32 v33, v16, v33
	v_fmamk_f32 v15, v33, 0xba800000, v15
	v_fmamk_f32 v13, v33, 0xba800000, v13
	v_fmamk_f32 v11, v33, 0xba800000, v11
	v_fmamk_f32 v9, v33, 0xba800000, v9
	v_fmamk_f32 v14, v33, 0xba800000, v14
	v_fmac_f32_e32 v12, 0xba800000, v33
	v_fmamk_f32 v10, v33, 0xba800000, v10
	v_fmac_f32_e32 v8, 0xba800000, v33
	v_fmamk_f32 v7, v33, 0xba800000, v7
	v_fmamk_f32 v5, v33, 0xba800000, v5
	v_mul_f32_e32 v16, v13, v13
	v_mul_f32_e32 v34, v15, v15
	v_mul_f32_e32 v35, v9, v9
	v_mul_f32_e32 v36, v11, v11
	v_fmamk_f32 v6, v33, 0xba800000, v6
	v_fmac_f32_e32 v4, 0xba800000, v33
	v_fmamk_f32 v3, v33, 0xba800000, v3
	v_fmamk_f32 v1, v33, 0xba800000, v1
	v_mul_f32_e32 v37, v5, v5
	v_mul_f32_e32 v38, v7, v7
	v_fmac_f32_e32 v16, v12, v12
	v_fmac_f32_e32 v34, v14, v14
	v_fmac_f32_e32 v35, v8, v8
	v_fmac_f32_e32 v36, v10, v10
	v_fmamk_f32 v2, v33, 0xba800000, v2
	v_fmac_f32_e32 v0, 0xba800000, v33
	v_mul_f32_e32 v39, v1, v1
	v_mul_f32_e32 v40, v3, v3
	v_fmac_f32_e32 v37, v4, v4
	v_fmac_f32_e32 v38, v6, v6
	v_add_f32_e32 v16, v16, v34
	v_add_f32_e32 v34, v35, v36
	v_fmac_f32_e32 v39, v0, v0
	v_fmac_f32_e32 v40, v2, v2
	v_add_f32_e32 v35, v37, v38
	v_add_f32_e32 v16, v16, v34
	v_add_f32_e32 v16, v35, v16
	v_add_f32_e32 v34, v39, v40
	v_add_f32_e32 v16, v34, v16
	ds_bpermute_b32 v34, v26, v16
	s_waitcnt lgkmcnt(0)
	v_add_f32_e32 v16, v16, v34
	ds_bpermute_b32 v34, v27, v16
	s_waitcnt lgkmcnt(0)
	v_add_f32_e32 v16, v16, v34
	ds_bpermute_b32 v34, v28, v16
	s_waitcnt lgkmcnt(0)
	v_add_f32_e32 v16, v16, v34
	ds_bpermute_b32 v34, v29, v16
	s_waitcnt lgkmcnt(0)
	v_add_f32_e32 v16, v16, v34
	ds_bpermute_b32 v34, v30, v16
	s_waitcnt lgkmcnt(0)
	v_add_f32_e32 v16, v16, v34
	ds_bpermute_b32 v34, v31, v16
	s_waitcnt lgkmcnt(0)
	v_add_f32_e32 v16, v16, v34
	v_fmamk_f32 v16, v16, 0x3a800000, v32
	v_rsq_f32_e32 v16, v16
	s_and_saveexec_b64 s[10:11], vcc
	s_cbranch_execz .Lln_nostat_a
	v_mul_f32_e32 v34, 0x3a800000, v33
	v_mov_b32_e32 v35, v16
	global_store_dwordx2 v17, v[34:35], s[0:1]
.Lln_nostat_a:
	s_or_b64 exec, exec, s[10:11]
	v_pk_mul_f32 v[14:15], v[14:15], v[16:17] op_sel_hi:[1,0]
	v_pk_mul_f32 v[12:13], v[12:13], v[16:17] op_sel_hi:[1,0]
	v_pk_mul_f32 v[10:11], v[10:11], v[16:17] op_sel_hi:[1,0]
	v_pk_mul_f32 v[8:9], v[8:9], v[16:17] op_sel_hi:[1,0]
	v_pk_mul_f32 v[6:7], v[6:7], v[16:17] op_sel_hi:[1,0]
	v_pk_mul_f32 v[4:5], v[4:5], v[16:17] op_sel_hi:[1,0]
	v_pk_mul_f32 v[2:3], v[2:3], v[16:17] op_sel_hi:[1,0]
	v_pk_mul_f32 v[0:1], v[0:1], v[16:17] op_sel_hi:[1,0]
	v_pk_fma_f32 v[14:15], v[14:15], v[98:99], v[114:115]
	v_pk_fma_f32 v[12:13], v[12:13], v[96:97], v[112:113]
	s_nop 0
	v_cvt_pk_bf16_f32 v12, v12, v13
	v_cvt_pk_bf16_f32 v13, v14, v15
	global_store_dwordx2 v[24:25], v[12:13], off
	v_pk_fma_f32 v[10:11], v[10:11], v[102:103], v[118:119]
	v_pk_fma_f32 v[8:9], v[8:9], v[100:101], v[116:117]
	s_nop 0
	v_cvt_pk_bf16_f32 v8, v8, v9
	v_cvt_pk_bf16_f32 v9, v10, v11
	global_store_dwordx2 v[24:25], v[8:9], off offset:512
	v_pk_fma_f32 v[6:7], v[6:7], v[106:107], v[122:123]
	v_pk_fma_f32 v[4:5], v[4:5], v[104:105], v[120:121]
	s_nop 0
	v_cvt_pk_bf16_f32 v4, v4, v5
	v_cvt_pk_bf16_f32 v5, v6, v7
	global_store_dwordx2 v[24:25], v[4:5], off offset:1024
	v_pk_fma_f32 v[2:3], v[2:3], v[110:111], v[126:127]
	v_pk_fma_f32 v[0:1], v[0:1], v[108:109], v[124:125]
	s_nop 0
	v_cvt_pk_bf16_f32 v0, v0, v1
	v_cvt_pk_bf16_f32 v1, v2, v3
	global_store_dwordx2 v[24:25], v[0:1], off offset:1536
	s_add_i32 s12, s12, s86
	s_add_u32 s0, s0, s4
	s_addc_u32 s1, s1, s5
	v_lshl_add_u64 v[24:25], v[24:25], 0, s[8:9]
	s_cmpk_lt_i32 s12, 0x4000
	s_cbranch_scc0 .LBB0_62
	s_add_i32 s13, s12, s86
	s_cmpk_lt_i32 s13, 0x4000
	s_cselect_b32 s14, s6, 0
	s_cselect_b32 s15, s7, 0
	v_lshl_add_u64 v[22:23], v[22:23], 0, s[14:15]
	global_load_dwordx4 v[12:15], v[22:23], off offset:-3072 nt
	global_load_dwordx4 v[8:11], v[22:23], off offset:-2048 nt
	global_load_dwordx4 v[4:7], v[22:23], off offset:-1024 nt
	global_load_dwordx4 v[0:3], v[22:23], off nt
	s_waitcnt vmcnt(9)
	v_mov_b32_e32 v34, v93
	v_mov_b32_e32 v35, v94
	v_mov_b32_e32 v36, v92
	v_mov_b32_e32 v37, v95
	v_mov_b32_e32 v38, v89
	v_mov_b32_e32 v39, v90
	v_mov_b32_e32 v40, v88
	v_mov_b32_e32 v41, v91
	v_pk_add_f32 v[34:35], v[34:35], v[36:37]
	v_pk_add_f32 v[36:37], v[38:39], v[40:41]
	v_add_f32_e32 v16, v34, v35
	v_pk_add_f32 v[34:35], v[36:37], v[36:37] op_sel:[0,1] op_sel_hi:[1,0]
	v_add_f32_e32 v42, v84, v85
	v_add_f32_e32 v44, v86, v87
	v_mov_b32_e32 v47, v80
	v_mov_b32_e32 v43, v82
	v_mov_b32_e32 v45, v83
	v_add_f32_e32 v46, 0, v16
	v_mov_b32_e32 v35, v81
	v_pk_add_f32 v[38:39], v[42:43], v[44:45]
	v_pk_add_f32 v[34:35], v[46:47], v[34:35]
	s_nop 0
	v_pk_add_f32 v[34:35], v[34:35], v[38:39]
	s_nop 0
	v_add_f32_e32 v16, v34, v35
	ds_bpermute_b32 v33, v26, v16
	s_waitcnt lgkmcnt(0)
	v_add_f32_e32 v16, v16, v33
	ds_bpermute_b32 v33, v27, v16
	s_waitcnt lgkmcnt(0)
	v_add_f32_e32 v16, v16, v33
	ds_bpermute_b32 v33, v28, v16
	s_waitcnt lgkmcnt(0)
	v_add_f32_e32 v16, v16, v33
	ds_bpermute_b32 v33, v29, v16
	s_waitcnt lgkmcnt(0)
	v_add_f32_e32 v16, v16, v33
	ds_bpermute_b32 v33, v30, v16
	s_waitcnt lgkmcnt(0)
	v_add_f32_e32 v16, v16, v33
	ds_bpermute_b32 v33, v31, v16
	s_waitcnt lgkmcnt(0)
	v_add_f32_e32 v33, v16, v33
	v_fmamk_f32 v95, v33, 0xba800000, v95
	v_fmamk_f32 v93, v33, 0xba800000, v93
	v_fmamk_f32 v91, v33, 0xba800000, v91
	v_fmamk_f32 v89, v33, 0xba800000, v89
	v_fmamk_f32 v94, v33, 0xba800000, v94
	v_fmac_f32_e32 v92, 0xba800000, v33
	v_fmamk_f32 v90, v33, 0xba800000, v90
	v_fmac_f32_e32 v88, 0xba800000, v33
	v_fmamk_f32 v87, v33, 0xba800000, v87
	v_fmamk_f32 v85, v33, 0xba800000, v85
	v_mul_f32_e32 v16, v93, v93
	v_mul_f32_e32 v34, v95, v95
	v_mul_f32_e32 v35, v89, v89
	v_mul_f32_e32 v36, v91, v91
	v_fmamk_f32 v86, v33, 0xba800000, v86
	v_fmac_f32_e32 v84, 0xba800000, v33
	v_fmamk_f32 v83, v33, 0xba800000, v83
	v_fmamk_f32 v81, v33, 0xba800000, v81
	v_mul_f32_e32 v37, v85, v85
	v_mul_f32_e32 v38, v87, v87
	v_fmac_f32_e32 v16, v92, v92
	v_fmac_f32_e32 v34, v94, v94
	v_fmac_f32_e32 v35, v88, v88
	v_fmac_f32_e32 v36, v90, v90
	v_fmamk_f32 v82, v33, 0xba800000, v82
	v_fmac_f32_e32 v80, 0xba800000, v33
	v_mul_f32_e32 v39, v81, v81
	v_mul_f32_e32 v40, v83, v83
	v_fmac_f32_e32 v37, v84, v84
	v_fmac_f32_e32 v38, v86, v86
	v_add_f32_e32 v16, v16, v34
	v_add_f32_e32 v34, v35, v36
	v_fmac_f32_e32 v39, v80, v80
	v_fmac_f32_e32 v40, v82, v82
	v_add_f32_e32 v35, v37, v38
	v_add_f32_e32 v16, v16, v34
	v_add_f32_e32 v16, v35, v16
	v_add_f32_e32 v34, v39, v40
	v_add_f32_e32 v16, v34, v16
	ds_bpermute_b32 v34, v26, v16
	s_waitcnt lgkmcnt(0)
	v_add_f32_e32 v16, v16, v34
	ds_bpermute_b32 v34, v27, v16
	s_waitcnt lgkmcnt(0)
	v_add_f32_e32 v16, v16, v34
	ds_bpermute_b32 v34, v28, v16
	s_waitcnt lgkmcnt(0)
	v_add_f32_e32 v16, v16, v34
	ds_bpermute_b32 v34, v29, v16
	s_waitcnt lgkmcnt(0)
	v_add_f32_e32 v16, v16, v34
	ds_bpermute_b32 v34, v30, v16
	s_waitcnt lgkmcnt(0)
	v_add_f32_e32 v16, v16, v34
	ds_bpermute_b32 v34, v31, v16
	s_waitcnt lgkmcnt(0)
	v_add_f32_e32 v16, v16, v34
	v_fmamk_f32 v16, v16, 0x3a800000, v32
	v_rsq_f32_e32 v16, v16
	s_and_saveexec_b64 s[10:11], vcc
	s_cbranch_execz .Lln_nostat_b
	v_mul_f32_e32 v34, 0x3a800000, v33
	v_mov_b32_e32 v35, v16
	global_store_dwordx2 v17, v[34:35], s[0:1]
.Lln_nostat_b:
	s_or_b64 exec, exec, s[10:11]
	v_pk_mul_f32 v[94:95], v[94:95], v[16:17] op_sel_hi:[1,0]
	v_pk_mul_f32 v[92:93], v[92:93], v[16:17] op_sel_hi:[1,0]
	v_pk_mul_f32 v[90:91], v[90:91], v[16:17] op_sel_hi:[1,0]
	v_pk_mul_f32 v[88:89], v[88:89], v[16:17] op_sel_hi:[1,0]
	v_pk_mul_f32 v[86:87], v[86:87], v[16:17] op_sel_hi:[1,0]
	v_pk_mul_f32 v[84:85], v[84:85], v[16:17] op_sel_hi:[1,0]
	v_pk_mul_f32 v[82:83], v[82:83], v[16:17] op_sel_hi:[1,0]
	v_pk_mul_f32 v[80:81], v[80:81], v[16:17] op_sel_hi:[1,0]
	v_pk_fma_f32 v[94:95], v[94:95], v[98:99], v[114:115]
	v_pk_fma_f32 v[92:93], v[92:93], v[96:97], v[112:113]
	s_nop 0
	v_cvt_pk_bf16_f32 v92, v92, v93
	v_cvt_pk_bf16_f32 v93, v94, v95
	global_store_dwordx2 v[24:25], v[92:93], off
	v_pk_fma_f32 v[90:91], v[90:91], v[102:103], v[118:119]
	v_pk_fma_f32 v[88:89], v[88:89], v[100:101], v[116:117]
	s_nop 0
	v_cvt_pk_bf16_f32 v88, v88, v89
	v_cvt_pk_bf16_f32 v89, v90, v91
	global_store_dwordx2 v[24:25], v[88:89], off offset:512
	v_pk_fma_f32 v[86:87], v[86:87], v[106:107], v[122:123]
	v_pk_fma_f32 v[84:85], v[84:85], v[104:105], v[120:121]
	s_nop 0
	v_cvt_pk_bf16_f32 v84, v84, v85
	v_cvt_pk_bf16_f32 v85, v86, v87
	global_store_dwordx2 v[24:25], v[84:85], off offset:1024
	v_pk_fma_f32 v[82:83], v[82:83], v[110:111], v[126:127]
	v_pk_fma_f32 v[80:81], v[80:81], v[108:109], v[124:125]
	s_nop 0
	v_cvt_pk_bf16_f32 v80, v80, v81
	v_cvt_pk_bf16_f32 v81, v82, v83
	global_store_dwordx2 v[24:25], v[80:81], off offset:1536
	s_add_i32 s12, s12, s86
	s_add_u32 s0, s0, s4
	s_addc_u32 s1, s1, s5
	v_lshl_add_u64 v[24:25], v[24:25], 0, s[8:9]
	s_cmpk_lt_i32 s12, 0x4000
	s_cbranch_scc0 .LBB0_62
	s_branch .Lln_loop

.LBB0_302:
	v_lshl_add_u64 v[60:61], v[44:45], 0, s[2:3]
	v_lshl_add_u64 v[62:63], v[42:43], 0, s[2:3]
	v_lshl_add_u64 v[64:65], v[40:41], 0, s[2:3]
	v_lshl_add_u64 v[66:67], v[38:39], 0, s[2:3]
	v_lshl_add_u64 v[68:69], v[36:37], 0, s[2:3]
	v_lshl_add_u64 v[70:71], v[34:35], 0, s[2:3]
	v_lshl_add_u64 v[72:73], v[32:33], 0, s[2:3]
	v_lshl_add_u64 v[74:75], v[30:31], 0, s[2:3]
	global_load_dword v128, v[60:61], off nt
	s_nop 0
	global_load_dword v129, v[62:63], off nt
	s_nop 0
	global_load_dword v130, v[64:65], off nt
	global_load_dword v131, v[66:67], off nt
	s_nop 0
	global_load_dword v132, v[68:69], off nt
	global_load_dword v133, v[70:71], off nt
	global_load_dword v134, v[72:73], off nt
	global_load_dword v135, v[74:75], off nt
	s_add_u32 s2, s2, 0x10000
	s_addc_u32 s3, s3, 0
	v_lshl_add_u64 v[60:61], v[44:45], 0, s[2:3]
	v_lshl_add_u64 v[62:63], v[42:43], 0, s[2:3]
	v_lshl_add_u64 v[64:65], v[40:41], 0, s[2:3]
	v_lshl_add_u64 v[66:67], v[38:39], 0, s[2:3]
	v_lshl_add_u64 v[68:69], v[36:37], 0, s[2:3]
	v_lshl_add_u64 v[70:71], v[34:35], 0, s[2:3]
	v_lshl_add_u64 v[72:73], v[32:33], 0, s[2:3]
	v_lshl_add_u64 v[74:75], v[30:31], 0, s[2:3]
	global_load_dword v136, v[60:61], off nt
	s_nop 0
	global_load_dword v137, v[62:63], off nt
	s_nop 0
	global_load_dword v138, v[64:65], off nt
	global_load_dword v139, v[66:67], off nt
	s_nop 0
	global_load_dword v140, v[68:69], off nt
	global_load_dword v141, v[70:71], off nt
	global_load_dword v142, v[72:73], off nt
	global_load_dword v143, v[74:75], off nt
	s_add_u32 s2, s2, 0x10000
	s_addc_u32 s3, s3, 0
	v_lshl_add_u64 v[60:61], v[44:45], 0, s[2:3]
	v_lshl_add_u64 v[62:63], v[42:43], 0, s[2:3]
	v_lshl_add_u64 v[64:65], v[40:41], 0, s[2:3]
	v_lshl_add_u64 v[66:67], v[38:39], 0, s[2:3]
	v_lshl_add_u64 v[68:69], v[36:37], 0, s[2:3]
	v_lshl_add_u64 v[70:71], v[34:35], 0, s[2:3]
	v_lshl_add_u64 v[72:73], v[32:33], 0, s[2:3]
	v_lshl_add_u64 v[74:75], v[30:31], 0, s[2:3]
	global_load_dword v144, v[60:61], off nt
	s_nop 0
	global_load_dword v145, v[62:63], off nt
	s_nop 0
	global_load_dword v146, v[64:65], off nt
	global_load_dword v147, v[66:67], off nt
	s_nop 0
	global_load_dword v148, v[68:69], off nt
	global_load_dword v149, v[70:71], off nt
	global_load_dword v150, v[72:73], off nt
	global_load_dword v151, v[74:75], off nt
	s_add_u32 s2, s2, 0x10000
	s_addc_u32 s3, s3, 0
	v_lshl_add_u64 v[60:61], v[44:45], 0, s[2:3]
	v_lshl_add_u64 v[62:63], v[42:43], 0, s[2:3]
	v_lshl_add_u64 v[64:65], v[40:41], 0, s[2:3]
	v_lshl_add_u64 v[66:67], v[38:39], 0, s[2:3]
	v_lshl_add_u64 v[68:69], v[36:37], 0, s[2:3]
	v_lshl_add_u64 v[70:71], v[34:35], 0, s[2:3]
	v_lshl_add_u64 v[72:73], v[32:33], 0, s[2:3]
	v_lshl_add_u64 v[74:75], v[30:31], 0, s[2:3]
	global_load_dword v152, v[60:61], off nt
	s_nop 0
	global_load_dword v153, v[62:63], off nt
	s_nop 0
	global_load_dword v154, v[64:65], off nt
	global_load_dword v155, v[66:67], off nt
	s_nop 0
	global_load_dword v156, v[68:69], off nt
	global_load_dword v157, v[70:71], off nt
	global_load_dword v158, v[72:73], off nt
	global_load_dword v159, v[74:75], off nt
	s_add_u32 s2, s2, 0x10000
	s_addc_u32 s3, s3, 0
	v_add_u32_e32 v68, 0x400, v0
	s_waitcnt vmcnt(30)
	ds_write2_b32 v0, v128, v129 offset1:66
	s_waitcnt vmcnt(28)
	ds_write2_b32 v0, v130, v131 offset0:132 offset1:198
	s_waitcnt vmcnt(26)
	ds_write2_b32 v68, v132, v133 offset0:8 offset1:74
	s_waitcnt vmcnt(24)
	ds_write2_b32 v68, v134, v135 offset0:140 offset1:206
	v_add_u32_e32 v0, 0x840, v0
	v_add_u32_e32 v68, 0x400, v0
	s_waitcnt vmcnt(22)
	ds_write2_b32 v0, v136, v137 offset1:66
	s_waitcnt vmcnt(20)
	ds_write2_b32 v0, v138, v139 offset0:132 offset1:198
	s_waitcnt vmcnt(18)
	ds_write2_b32 v68, v140, v141 offset0:8 offset1:74
	s_waitcnt vmcnt(16)
	ds_write2_b32 v68, v142, v143 offset0:140 offset1:206
	v_add_u32_e32 v0, 0x840, v0
	v_add_u32_e32 v68, 0x400, v0
	s_waitcnt vmcnt(14)
	ds_write2_b32 v0, v144, v145 offset1:66
	s_waitcnt vmcnt(12)
	ds_write2_b32 v0, v146, v147 offset0:132 offset1:198
	s_waitcnt vmcnt(10)
	ds_write2_b32 v68, v148, v149 offset0:8 offset1:74
	s_waitcnt vmcnt(8)
	ds_write2_b32 v68, v150, v151 offset0:140 offset1:206
	v_add_u32_e32 v0, 0x840, v0
	v_add_u32_e32 v68, 0x400, v0
	s_waitcnt vmcnt(6)
	ds_write2_b32 v0, v152, v153 offset1:66
	s_waitcnt vmcnt(4)
	ds_write2_b32 v0, v154, v155 offset0:132 offset1:198
	s_waitcnt vmcnt(2)
	ds_write2_b32 v68, v156, v157 offset0:8 offset1:74
	s_waitcnt vmcnt(0)
	ds_write2_b32 v68, v158, v159 offset0:140 offset1:206
	v_add_u32_e32 v0, 0x840, v0
	s_lshl_b32 s0, s8, 1
	s_lshl_b32 s2, s8, 5
	s_waitcnt lgkmcnt(0)
	s_add_i32 s0, s0, 0x7fffb200
	s_and_b32 s2, s2, 0x3e0
	ds_read2_b32 v[34:35], v47 offset0:33 offset1:41
	ds_read2_b32 v[36:37], v47 offset1:8
	ds_read2_b32 v[38:39], v47 offset0:66 offset1:74
	ds_read2_b32 v[40:41], v47 offset0:99 offset1:107
	ds_read2_b32 v[42:43], v47 offset0:132 offset1:140
	ds_read2_b32 v[44:45], v47 offset0:165 offset1:173
	ds_read2_b32 v[60:61], v47 offset0:198 offset1:206
	ds_read2_b32 v[62:63], v47 offset0:231 offset1:239
	s_and_b32 s0, s0, 0x7fffffc0
	v_or_b32_e32 v0, s2, v46
	s_lshl_b32 s0, s0, 1
	v_mul_u32_u24_e32 v0, 0xb00, v0
	v_lshl_add_u64 v[64:65], v[2:3], 0, s[0:1]
	v_lshlrev_b32_e32 v0, 1, v0
	v_lshl_add_u64 v[66:67], v[64:65], 0, v[0:1]
	v_or_b32_e32 v0, s2, v48
	s_waitcnt lgkmcnt(6)
	v_cvt_pk_bf16_f32 v30, v36, v34
	s_waitcnt lgkmcnt(4)
	v_cvt_pk_bf16_f32 v31, v38, v40
	s_waitcnt lgkmcnt(2)
	v_cvt_pk_bf16_f32 v32, v42, v44
	s_waitcnt lgkmcnt(0)
	v_cvt_pk_bf16_f32 v33, v60, v62
	v_mul_u32_u24_e32 v0, 0xb00, v0
	global_store_dwordx4 v[66:67], v[30:33], off
	v_lshlrev_b32_e32 v0, 1, v0
	s_nop 0
	v_cvt_pk_bf16_f32 v30, v37, v35
	v_cvt_pk_bf16_f32 v31, v39, v41
	v_cvt_pk_bf16_f32 v32, v43, v45
	v_cvt_pk_bf16_f32 v33, v61, v63
	v_lshl_add_u64 v[34:35], v[64:65], 0, v[0:1]
	ds_read2_b32 v[36:37], v47 offset0:16 offset1:24
	ds_read2_b32 v[38:39], v47 offset0:49 offset1:57
	ds_read2_b32 v[40:41], v47 offset0:82 offset1:90
	ds_read2_b32 v[42:43], v47 offset0:115 offset1:123
	ds_read2_b32 v[44:45], v47 offset0:148 offset1:156
	ds_read2_b32 v[60:61], v47 offset0:181 offset1:189
	ds_read2_b32 v[62:63], v47 offset0:214 offset1:222
	ds_read2_b32 v[66:67], v47 offset0:247 offset1:255
	v_or_b32_e32 v0, s2, v49
	v_mul_u32_u24_e32 v0, 0xb00, v0
	v_lshlrev_b32_e32 v0, 1, v0
	global_store_dwordx4 v[34:35], v[30:33], off
	v_lshl_add_u64 v[34:35], v[64:65], 0, v[0:1]
	v_or_b32_e32 v0, s2, v50
	v_mul_u32_u24_e32 v0, 0xb00, v0
	s_waitcnt lgkmcnt(6)
	v_cvt_pk_bf16_f32 v30, v36, v38
	s_waitcnt lgkmcnt(4)
	v_cvt_pk_bf16_f32 v31, v40, v42
	s_waitcnt lgkmcnt(2)
	v_cvt_pk_bf16_f32 v32, v44, v60
	s_waitcnt lgkmcnt(0)
	v_cvt_pk_bf16_f32 v33, v62, v66
	v_lshlrev_b32_e32 v0, 1, v0
	global_store_dwordx4 v[34:35], v[30:33], off
	v_lshl_add_u64 v[34:35], v[64:65], 0, v[0:1]
	s_mov_b64 s[2:3], 0
	v_cvt_pk_bf16_f32 v30, v37, v39
	v_cvt_pk_bf16_f32 v31, v41, v43
	v_cvt_pk_bf16_f32 v32, v45, v61
	v_cvt_pk_bf16_f32 v33, v63, v67
	global_store_dwordx4 v[34:35], v[30:33], off
	s_waitcnt lgkmcnt(0)

.LBB0_306:
	v_lshl_add_u64 v[40:41], v[38:39], 0, s[2:3]
	v_add_co_u32_e32 v64, vcc, 0xb000, v40
	global_load_dword v128, v[40:41], off nt
	s_nop 0
	v_addc_co_u32_e32 v65, vcc, 0, v41, vcc
	v_add_co_u32_e32 v66, vcc, 0x16000, v40
	global_load_dword v129, v[64:65], off nt
	s_nop 0
	v_addc_co_u32_e32 v67, vcc, 0, v41, vcc
	v_add_co_u32_e32 v40, vcc, 0x21000, v40
	v_lshl_add_u64 v[42:43], v[36:37], 0, s[2:3]
	v_lshl_add_u64 v[44:45], v[34:35], 0, s[2:3]
	v_addc_co_u32_e32 v41, vcc, 0, v41, vcc
	v_lshl_add_u64 v[60:61], v[32:33], 0, s[2:3]
	v_lshl_add_u64 v[62:63], v[30:31], 0, s[2:3]
	global_load_dword v130, v[66:67], off nt
	s_nop 0
	global_load_dword v131, v[40:41], off nt
	s_nop 0
	global_load_dword v132, v[42:43], off nt
	s_nop 0
	global_load_dword v133, v[44:45], off nt
	global_load_dword v134, v[60:61], off nt
	s_nop 0
	global_load_dword v135, v[62:63], off nt
	s_add_u32 s2, s2, 0x58000
	s_addc_u32 s3, s3, 0
	v_lshl_add_u64 v[40:41], v[38:39], 0, s[2:3]
	v_add_co_u32_e32 v64, vcc, 0xb000, v40
	global_load_dword v136, v[40:41], off nt
	s_nop 0
	v_addc_co_u32_e32 v65, vcc, 0, v41, vcc
	v_add_co_u32_e32 v66, vcc, 0x16000, v40
	global_load_dword v137, v[64:65], off nt
	s_nop 0
	v_addc_co_u32_e32 v67, vcc, 0, v41, vcc
	v_add_co_u32_e32 v40, vcc, 0x21000, v40
	v_lshl_add_u64 v[42:43], v[36:37], 0, s[2:3]
	v_lshl_add_u64 v[44:45], v[34:35], 0, s[2:3]
	v_addc_co_u32_e32 v41, vcc, 0, v41, vcc
	v_lshl_add_u64 v[60:61], v[32:33], 0, s[2:3]
	v_lshl_add_u64 v[62:63], v[30:31], 0, s[2:3]
	global_load_dword v138, v[66:67], off nt
	s_nop 0
	global_load_dword v139, v[40:41], off nt
	s_nop 0
	global_load_dword v140, v[42:43], off nt
	s_nop 0
	global_load_dword v141, v[44:45], off nt
	global_load_dword v142, v[60:61], off nt
	s_nop 0
	global_load_dword v143, v[62:63], off nt
	s_add_u32 s2, s2, 0x58000
	s_addc_u32 s3, s3, 0
	v_lshl_add_u64 v[40:41], v[38:39], 0, s[2:3]
	v_add_co_u32_e32 v64, vcc, 0xb000, v40
	global_load_dword v144, v[40:41], off nt
	s_nop 0
	v_addc_co_u32_e32 v65, vcc, 0, v41, vcc
	v_add_co_u32_e32 v66, vcc, 0x16000, v40
	global_load_dword v145, v[64:65], off nt
	s_nop 0
	v_addc_co_u32_e32 v67, vcc, 0, v41, vcc
	v_add_co_u32_e32 v40, vcc, 0x21000, v40
	v_lshl_add_u64 v[42:43], v[36:37], 0, s[2:3]
	v_lshl_add_u64 v[44:45], v[34:35], 0, s[2:3]
	v_addc_co_u32_e32 v41, vcc, 0, v41, vcc
	v_lshl_add_u64 v[60:61], v[32:33], 0, s[2:3]
	v_lshl_add_u64 v[62:63], v[30:31], 0, s[2:3]
	global_load_dword v146, v[66:67], off nt
	s_nop 0
	global_load_dword v147, v[40:41], off nt
	s_nop 0
	global_load_dword v148, v[42:43], off nt
	s_nop 0
	global_load_dword v149, v[44:45], off nt
	global_load_dword v150, v[60:61], off nt
	s_nop 0
	global_load_dword v151, v[62:63], off nt
	s_add_u32 s2, s2, 0x58000
	s_addc_u32 s3, s3, 0
	v_lshl_add_u64 v[40:41], v[38:39], 0, s[2:3]
	v_add_co_u32_e32 v64, vcc, 0xb000, v40
	global_load_dword v152, v[40:41], off nt
	s_nop 0
	v_addc_co_u32_e32 v65, vcc, 0, v41, vcc
	v_add_co_u32_e32 v66, vcc, 0x16000, v40
	global_load_dword v153, v[64:65], off nt
	s_nop 0
	v_addc_co_u32_e32 v67, vcc, 0, v41, vcc
	v_add_co_u32_e32 v40, vcc, 0x21000, v40
	v_lshl_add_u64 v[42:43], v[36:37], 0, s[2:3]
	v_lshl_add_u64 v[44:45], v[34:35], 0, s[2:3]
	v_addc_co_u32_e32 v41, vcc, 0, v41, vcc
	v_lshl_add_u64 v[60:61], v[32:33], 0, s[2:3]
	v_lshl_add_u64 v[62:63], v[30:31], 0, s[2:3]
	global_load_dword v154, v[66:67], off nt
	s_nop 0
	global_load_dword v155, v[40:41], off nt
	s_nop 0
	global_load_dword v156, v[42:43], off nt
	s_nop 0
	global_load_dword v157, v[44:45], off nt
	global_load_dword v158, v[60:61], off nt
	s_nop 0
	global_load_dword v159, v[62:63], off nt
	s_add_u32 s2, s2, 0x58000
	s_addc_u32 s3, s3, 0
	v_add_u32_e32 v45, 0x400, v0
	s_waitcnt vmcnt(30)
	ds_write2_b32 v0, v128, v129 offset1:66
	s_waitcnt vmcnt(28)
	ds_write2_b32 v0, v130, v131 offset0:132 offset1:198
	s_waitcnt vmcnt(26)
	ds_write2_b32 v45, v132, v133 offset0:8 offset1:74
	s_waitcnt vmcnt(24)
	ds_write2_b32 v45, v134, v135 offset0:140 offset1:206
	v_add_u32_e32 v0, 0x840, v0
	v_add_u32_e32 v45, 0x400, v0
	s_waitcnt vmcnt(22)
	ds_write2_b32 v0, v136, v137 offset1:66
	s_waitcnt vmcnt(20)
	ds_write2_b32 v0, v138, v139 offset0:132 offset1:198
	s_waitcnt vmcnt(18)
	ds_write2_b32 v45, v140, v141 offset0:8 offset1:74
	s_waitcnt vmcnt(16)
	ds_write2_b32 v45, v142, v143 offset0:140 offset1:206
	v_add_u32_e32 v0, 0x840, v0
	v_add_u32_e32 v45, 0x400, v0
	s_waitcnt vmcnt(14)
	ds_write2_b32 v0, v144, v145 offset1:66
	s_waitcnt vmcnt(12)
	ds_write2_b32 v0, v146, v147 offset0:132 offset1:198
	s_waitcnt vmcnt(10)
	ds_write2_b32 v45, v148, v149 offset0:8 offset1:74
	s_waitcnt vmcnt(8)
	ds_write2_b32 v45, v150, v151 offset0:140 offset1:206
	v_add_u32_e32 v0, 0x840, v0
	v_add_u32_e32 v45, 0x400, v0
	s_waitcnt vmcnt(6)
	ds_write2_b32 v0, v152, v153 offset1:66
	s_waitcnt vmcnt(4)
	ds_write2_b32 v0, v154, v155 offset0:132 offset1:198
	s_waitcnt vmcnt(2)
	ds_write2_b32 v45, v156, v157 offset0:8 offset1:74
	s_waitcnt vmcnt(0)
	ds_write2_b32 v45, v158, v159 offset0:140 offset1:206
	v_add_u32_e32 v0, 0x840, v0
	s_waitcnt lgkmcnt(0)
	ds_read2_b32 v[34:35], v47 offset0:33 offset1:41
	ds_read2_b32 v[36:37], v47 offset1:8
	ds_read2_b32 v[38:39], v47 offset0:66 offset1:74
	ds_read2_b32 v[40:41], v47 offset0:99 offset1:107
	ds_read2_b32 v[42:43], v47 offset0:132 offset1:140
	ds_read2_b32 v[44:45], v47 offset0:165 offset1:173
	ds_read2_b32 v[60:61], v47 offset0:198 offset1:206
	ds_read2_b32 v[62:63], v47 offset0:231 offset1:239
	s_and_b32 s0, 0xffff, s6
	s_lshl_b32 s0, s0, 1
	v_or_b32_e32 v0, s5, v46
	v_lshl_add_u64 v[64:65], v[4:5], 0, s[0:1]
	v_lshlrev_b32_e32 v0, 11, v0
	s_waitcnt lgkmcnt(6)
	v_cvt_pk_bf16_f32 v30, v36, v34
	s_waitcnt lgkmcnt(4)
	v_cvt_pk_bf16_f32 v31, v38, v40
	s_waitcnt lgkmcnt(2)
	v_cvt_pk_bf16_f32 v32, v42, v44
	s_waitcnt lgkmcnt(0)
	v_cvt_pk_bf16_f32 v33, v60, v62
	v_lshl_add_u64 v[66:67], v[64:65], 0, v[0:1]
	global_store_dwordx4 v[66:67], v[30:33], off
	v_or_b32_e32 v0, s5, v48
	v_lshlrev_b32_e32 v0, 11, v0
	v_cvt_pk_bf16_f32 v30, v37, v35
	v_cvt_pk_bf16_f32 v31, v39, v41
	v_cvt_pk_bf16_f32 v32, v43, v45
	v_cvt_pk_bf16_f32 v33, v61, v63
	ds_read2_b32 v[36:37], v47 offset0:49 offset1:57
	ds_read2_b32 v[38:39], v47 offset0:16 offset1:24
	ds_read2_b32 v[40:41], v47 offset0:82 offset1:90
	ds_read2_b32 v[42:43], v47 offset0:115 offset1:123
	ds_read2_b32 v[44:45], v47 offset0:148 offset1:156
	ds_read2_b32 v[60:61], v47 offset0:181 offset1:189
	ds_read2_b32 v[62:63], v47 offset0:214 offset1:222
	ds_read2_b32 v[66:67], v47 offset0:247 offset1:255
	v_lshl_add_u64 v[34:35], v[64:65], 0, v[0:1]
	v_or_b32_e32 v0, s5, v49
	v_lshlrev_b32_e32 v0, 11, v0
	global_store_dwordx4 v[34:35], v[30:33], off
	v_lshl_add_u64 v[34:35], v[64:65], 0, v[0:1]
	v_or_b32_e32 v0, s5, v50
	s_waitcnt lgkmcnt(6)
	v_cvt_pk_bf16_f32 v30, v38, v36
	s_waitcnt lgkmcnt(4)
	v_cvt_pk_bf16_f32 v31, v40, v42
	s_waitcnt lgkmcnt(2)
	v_cvt_pk_bf16_f32 v32, v44, v60
	s_waitcnt lgkmcnt(0)
	v_cvt_pk_bf16_f32 v33, v62, v66
	v_lshlrev_b32_e32 v0, 11, v0
	global_store_dwordx4 v[34:35], v[30:33], off
	v_lshl_add_u64 v[34:35], v[64:65], 0, v[0:1]
	s_nop 0
	v_cvt_pk_bf16_f32 v30, v39, v37
	v_cvt_pk_bf16_f32 v31, v41, v43
	v_cvt_pk_bf16_f32 v32, v45, v61
	v_cvt_pk_bf16_f32 v33, v63, v67
	global_store_dwordx4 v[34:35], v[30:33], off
	s_waitcnt lgkmcnt(0)

.LBB0_311:
	v_lshl_add_u64 v[60:61], v[44:45], 0, s[2:3]
	v_lshl_add_u64 v[62:63], v[42:43], 0, s[2:3]
	v_lshl_add_u64 v[64:65], v[40:41], 0, s[2:3]
	v_lshl_add_u64 v[66:67], v[38:39], 0, s[2:3]
	v_lshl_add_u64 v[68:69], v[36:37], 0, s[2:3]
	v_lshl_add_u64 v[70:71], v[34:35], 0, s[2:3]
	v_lshl_add_u64 v[72:73], v[32:33], 0, s[2:3]
	v_lshl_add_u64 v[74:75], v[30:31], 0, s[2:3]
	global_load_dword v128, v[60:61], off nt
	s_nop 0
	global_load_dword v129, v[62:63], off nt
	s_nop 0
	global_load_dword v130, v[64:65], off nt
	global_load_dword v131, v[66:67], off nt
	s_nop 0
	global_load_dword v132, v[68:69], off nt
	global_load_dword v133, v[70:71], off nt
	global_load_dword v134, v[72:73], off nt
	global_load_dword v135, v[74:75], off nt
	s_add_u32 s2, s2, 0x10000
	s_addc_u32 s3, s3, 0
	v_lshl_add_u64 v[60:61], v[44:45], 0, s[2:3]
	v_lshl_add_u64 v[62:63], v[42:43], 0, s[2:3]
	v_lshl_add_u64 v[64:65], v[40:41], 0, s[2:3]
	v_lshl_add_u64 v[66:67], v[38:39], 0, s[2:3]
	v_lshl_add_u64 v[68:69], v[36:37], 0, s[2:3]
	v_lshl_add_u64 v[70:71], v[34:35], 0, s[2:3]
	v_lshl_add_u64 v[72:73], v[32:33], 0, s[2:3]
	v_lshl_add_u64 v[74:75], v[30:31], 0, s[2:3]
	global_load_dword v136, v[60:61], off nt
	s_nop 0
	global_load_dword v137, v[62:63], off nt
	s_nop 0
	global_load_dword v138, v[64:65], off nt
	global_load_dword v139, v[66:67], off nt
	s_nop 0
	global_load_dword v140, v[68:69], off nt
	global_load_dword v141, v[70:71], off nt
	global_load_dword v142, v[72:73], off nt
	global_load_dword v143, v[74:75], off nt
	s_add_u32 s2, s2, 0x10000
	s_addc_u32 s3, s3, 0
	v_lshl_add_u64 v[60:61], v[44:45], 0, s[2:3]
	v_lshl_add_u64 v[62:63], v[42:43], 0, s[2:3]
	v_lshl_add_u64 v[64:65], v[40:41], 0, s[2:3]
	v_lshl_add_u64 v[66:67], v[38:39], 0, s[2:3]
	v_lshl_add_u64 v[68:69], v[36:37], 0, s[2:3]
	v_lshl_add_u64 v[70:71], v[34:35], 0, s[2:3]
	v_lshl_add_u64 v[72:73], v[32:33], 0, s[2:3]
	v_lshl_add_u64 v[74:75], v[30:31], 0, s[2:3]
	global_load_dword v144, v[60:61], off nt
	s_nop 0
	global_load_dword v145, v[62:63], off nt
	s_nop 0
	global_load_dword v146, v[64:65], off nt
	global_load_dword v147, v[66:67], off nt
	s_nop 0
	global_load_dword v148, v[68:69], off nt
	global_load_dword v149, v[70:71], off nt
	global_load_dword v150, v[72:73], off nt
	global_load_dword v151, v[74:75], off nt
	s_add_u32 s2, s2, 0x10000
	s_addc_u32 s3, s3, 0
	v_lshl_add_u64 v[60:61], v[44:45], 0, s[2:3]
	v_lshl_add_u64 v[62:63], v[42:43], 0, s[2:3]
	v_lshl_add_u64 v[64:65], v[40:41], 0, s[2:3]
	v_lshl_add_u64 v[66:67], v[38:39], 0, s[2:3]
	v_lshl_add_u64 v[68:69], v[36:37], 0, s[2:3]
	v_lshl_add_u64 v[70:71], v[34:35], 0, s[2:3]
	v_lshl_add_u64 v[72:73], v[32:33], 0, s[2:3]
	v_lshl_add_u64 v[74:75], v[30:31], 0, s[2:3]
	global_load_dword v152, v[60:61], off nt
	s_nop 0
	global_load_dword v153, v[62:63], off nt
	s_nop 0
	global_load_dword v154, v[64:65], off nt
	global_load_dword v155, v[66:67], off nt
	s_nop 0
	global_load_dword v156, v[68:69], off nt
	global_load_dword v157, v[70:71], off nt
	global_load_dword v158, v[72:73], off nt
	global_load_dword v159, v[74:75], off nt
	s_add_u32 s2, s2, 0x10000
	s_addc_u32 s3, s3, 0
	v_add_u32_e32 v68, 0x400, v0
	s_waitcnt vmcnt(30)
	ds_write2_b32 v0, v128, v129 offset1:66
	s_waitcnt vmcnt(28)
	ds_write2_b32 v0, v130, v131 offset0:132 offset1:198
	s_waitcnt vmcnt(26)
	ds_write2_b32 v68, v132, v133 offset0:8 offset1:74
	s_waitcnt vmcnt(24)
	ds_write2_b32 v68, v134, v135 offset0:140 offset1:206
	v_add_u32_e32 v0, 0x840, v0
	v_add_u32_e32 v68, 0x400, v0
	s_waitcnt vmcnt(22)
	ds_write2_b32 v0, v136, v137 offset1:66
	s_waitcnt vmcnt(20)
	ds_write2_b32 v0, v138, v139 offset0:132 offset1:198
	s_waitcnt vmcnt(18)
	ds_write2_b32 v68, v140, v141 offset0:8 offset1:74
	s_waitcnt vmcnt(16)
	ds_write2_b32 v68, v142, v143 offset0:140 offset1:206
	v_add_u32_e32 v0, 0x840, v0
	v_add_u32_e32 v68, 0x400, v0
	s_waitcnt vmcnt(14)
	ds_write2_b32 v0, v144, v145 offset1:66
	s_waitcnt vmcnt(12)
	ds_write2_b32 v0, v146, v147 offset0:132 offset1:198
	s_waitcnt vmcnt(10)
	ds_write2_b32 v68, v148, v149 offset0:8 offset1:74
	s_waitcnt vmcnt(8)
	ds_write2_b32 v68, v150, v151 offset0:140 offset1:206
	v_add_u32_e32 v0, 0x840, v0
	v_add_u32_e32 v68, 0x400, v0
	s_waitcnt vmcnt(6)
	ds_write2_b32 v0, v152, v153 offset1:66
	s_waitcnt vmcnt(4)
	ds_write2_b32 v0, v154, v155 offset0:132 offset1:198
	s_waitcnt vmcnt(2)
	ds_write2_b32 v68, v156, v157 offset0:8 offset1:74
	s_waitcnt vmcnt(0)
	ds_write2_b32 v68, v158, v159 offset0:140 offset1:206
	v_add_u32_e32 v0, 0x840, v0
	s_waitcnt lgkmcnt(0)
	s_lshl_b32 s0, s8, 1
	ds_read2_b32 v[34:35], v47 offset0:33 offset1:41
	ds_read2_b32 v[36:37], v47 offset1:8
	ds_read2_b32 v[38:39], v47 offset0:66 offset1:74
	ds_read2_b32 v[40:41], v47 offset0:99 offset1:107
	ds_read2_b32 v[42:43], v47 offset0:132 offset1:140
	ds_read2_b32 v[44:45], v47 offset0:165 offset1:173
	ds_read2_b32 v[60:61], v47 offset0:198 offset1:206
	ds_read2_b32 v[62:63], v47 offset0:231 offset1:239
	s_add_i32 s0, s0, 0x7fffcc00
	s_lshl_b32 s2, s8, 5
	s_and_b32 s0, s0, 0x7fffffc0
	s_and_b32 s2, s2, 0x3e0
	s_lshl_b32 s0, s0, 1
	v_or_b32_e32 v0, s2, v46
	v_lshl_add_u64 v[64:65], v[6:7], 0, s[0:1]
	v_lshlrev_b32_e32 v0, 11, v0
	s_waitcnt lgkmcnt(6)
	v_cvt_pk_bf16_f32 v30, v36, v34
	s_waitcnt lgkmcnt(4)
	v_cvt_pk_bf16_f32 v31, v38, v40
	s_waitcnt lgkmcnt(2)
	v_cvt_pk_bf16_f32 v32, v42, v44
	s_waitcnt lgkmcnt(0)
	v_cvt_pk_bf16_f32 v33, v60, v62
	v_lshl_add_u64 v[66:67], v[64:65], 0, v[0:1]
	global_store_dwordx4 v[66:67], v[30:33], off
	v_or_b32_e32 v0, s2, v48
	v_lshlrev_b32_e32 v0, 11, v0
	v_cvt_pk_bf16_f32 v30, v37, v35
	v_cvt_pk_bf16_f32 v31, v39, v41
	v_cvt_pk_bf16_f32 v32, v43, v45
	v_cvt_pk_bf16_f32 v33, v61, v63
	ds_read2_b32 v[36:37], v47 offset0:49 offset1:57
	ds_read2_b32 v[38:39], v47 offset0:16 offset1:24
	ds_read2_b32 v[40:41], v47 offset0:82 offset1:90
	ds_read2_b32 v[42:43], v47 offset0:115 offset1:123
	ds_read2_b32 v[44:45], v47 offset0:148 offset1:156
	ds_read2_b32 v[60:61], v47 offset0:181 offset1:189
	ds_read2_b32 v[62:63], v47 offset0:214 offset1:222
	ds_read2_b32 v[66:67], v47 offset0:247 offset1:255
	v_lshl_add_u64 v[34:35], v[64:65], 0, v[0:1]
	v_or_b32_e32 v0, s2, v49
	v_lshlrev_b32_e32 v0, 11, v0
	global_store_dwordx4 v[34:35], v[30:33], off
	v_lshl_add_u64 v[34:35], v[64:65], 0, v[0:1]
	v_or_b32_e32 v0, s2, v50
	s_waitcnt lgkmcnt(6)
	v_cvt_pk_bf16_f32 v30, v38, v36
	s_waitcnt lgkmcnt(4)
	v_cvt_pk_bf16_f32 v31, v40, v42
	s_waitcnt lgkmcnt(2)
	v_cvt_pk_bf16_f32 v32, v44, v60
	s_waitcnt lgkmcnt(0)
	v_cvt_pk_bf16_f32 v33, v62, v66
	v_lshlrev_b32_e32 v0, 11, v0
	global_store_dwordx4 v[34:35], v[30:33], off
	v_lshl_add_u64 v[34:35], v[64:65], 0, v[0:1]
	s_nop 0
	v_cvt_pk_bf16_f32 v30, v39, v37
	v_cvt_pk_bf16_f32 v31, v41, v43
	v_cvt_pk_bf16_f32 v32, v45, v61
	v_cvt_pk_bf16_f32 v33, v63, v67
	global_store_dwordx4 v[34:35], v[30:33], off
	s_waitcnt lgkmcnt(0)

.LBB0_316:
	v_lshl_add_u64 v[60:61], v[44:45], 0, s[2:3]
	v_lshl_add_u64 v[62:63], v[42:43], 0, s[2:3]
	v_lshl_add_u64 v[64:65], v[40:41], 0, s[2:3]
	v_lshl_add_u64 v[66:67], v[38:39], 0, s[2:3]
	v_lshl_add_u64 v[68:69], v[36:37], 0, s[2:3]
	v_lshl_add_u64 v[70:71], v[34:35], 0, s[2:3]
	v_lshl_add_u64 v[72:73], v[32:33], 0, s[2:3]
	v_lshl_add_u64 v[74:75], v[30:31], 0, s[2:3]
	global_load_dword v128, v[60:61], off nt
	s_nop 0
	global_load_dword v129, v[62:63], off nt
	s_nop 0
	global_load_dword v130, v[64:65], off nt
	global_load_dword v131, v[66:67], off nt
	s_nop 0
	global_load_dword v132, v[68:69], off nt
	global_load_dword v133, v[70:71], off nt
	global_load_dword v134, v[72:73], off nt
	global_load_dword v135, v[74:75], off nt
	s_add_u32 s2, s2, 0x10000
	s_addc_u32 s3, s3, 0
	v_lshl_add_u64 v[60:61], v[44:45], 0, s[2:3]
	v_lshl_add_u64 v[62:63], v[42:43], 0, s[2:3]
	v_lshl_add_u64 v[64:65], v[40:41], 0, s[2:3]
	v_lshl_add_u64 v[66:67], v[38:39], 0, s[2:3]
	v_lshl_add_u64 v[68:69], v[36:37], 0, s[2:3]
	v_lshl_add_u64 v[70:71], v[34:35], 0, s[2:3]
	v_lshl_add_u64 v[72:73], v[32:33], 0, s[2:3]
	v_lshl_add_u64 v[74:75], v[30:31], 0, s[2:3]
	global_load_dword v136, v[60:61], off nt
	s_nop 0
	global_load_dword v137, v[62:63], off nt
	s_nop 0
	global_load_dword v138, v[64:65], off nt
	global_load_dword v139, v[66:67], off nt
	s_nop 0
	global_load_dword v140, v[68:69], off nt
	global_load_dword v141, v[70:71], off nt
	global_load_dword v142, v[72:73], off nt
	global_load_dword v143, v[74:75], off nt
	s_add_u32 s2, s2, 0x10000
	s_addc_u32 s3, s3, 0
	v_lshl_add_u64 v[60:61], v[44:45], 0, s[2:3]
	v_lshl_add_u64 v[62:63], v[42:43], 0, s[2:3]
	v_lshl_add_u64 v[64:65], v[40:41], 0, s[2:3]
	v_lshl_add_u64 v[66:67], v[38:39], 0, s[2:3]
	v_lshl_add_u64 v[68:69], v[36:37], 0, s[2:3]
	v_lshl_add_u64 v[70:71], v[34:35], 0, s[2:3]
	v_lshl_add_u64 v[72:73], v[32:33], 0, s[2:3]
	v_lshl_add_u64 v[74:75], v[30:31], 0, s[2:3]
	global_load_dword v144, v[60:61], off nt
	s_nop 0
	global_load_dword v145, v[62:63], off nt
	s_nop 0
	global_load_dword v146, v[64:65], off nt
	global_load_dword v147, v[66:67], off nt
	s_nop 0
	global_load_dword v148, v[68:69], off nt
	global_load_dword v149, v[70:71], off nt
	global_load_dword v150, v[72:73], off nt
	global_load_dword v151, v[74:75], off nt
	s_add_u32 s2, s2, 0x10000
	s_addc_u32 s3, s3, 0
	v_lshl_add_u64 v[60:61], v[44:45], 0, s[2:3]
	v_lshl_add_u64 v[62:63], v[42:43], 0, s[2:3]
	v_lshl_add_u64 v[64:65], v[40:41], 0, s[2:3]
	v_lshl_add_u64 v[66:67], v[38:39], 0, s[2:3]
	v_lshl_add_u64 v[68:69], v[36:37], 0, s[2:3]
	v_lshl_add_u64 v[70:71], v[34:35], 0, s[2:3]
	v_lshl_add_u64 v[72:73], v[32:33], 0, s[2:3]
	v_lshl_add_u64 v[74:75], v[30:31], 0, s[2:3]
	global_load_dword v152, v[60:61], off nt
	s_nop 0
	global_load_dword v153, v[62:63], off nt
	s_nop 0
	global_load_dword v154, v[64:65], off nt
	global_load_dword v155, v[66:67], off nt
	s_nop 0
	global_load_dword v156, v[68:69], off nt
	global_load_dword v157, v[70:71], off nt
	global_load_dword v158, v[72:73], off nt
	global_load_dword v159, v[74:75], off nt
	s_add_u32 s2, s2, 0x10000
	s_addc_u32 s3, s3, 0
	v_add_u32_e32 v68, 0x400, v0
	s_waitcnt vmcnt(30)
	ds_write2_b32 v0, v128, v129 offset1:66
	s_waitcnt vmcnt(28)
	ds_write2_b32 v0, v130, v131 offset0:132 offset1:198
	s_waitcnt vmcnt(26)
	ds_write2_b32 v68, v132, v133 offset0:8 offset1:74
	s_waitcnt vmcnt(24)
	ds_write2_b32 v68, v134, v135 offset0:140 offset1:206
	v_add_u32_e32 v0, 0x840, v0
	v_add_u32_e32 v68, 0x400, v0
	s_waitcnt vmcnt(22)
	ds_write2_b32 v0, v136, v137 offset1:66
	s_waitcnt vmcnt(20)
	ds_write2_b32 v0, v138, v139 offset0:132 offset1:198
	s_waitcnt vmcnt(18)
	ds_write2_b32 v68, v140, v141 offset0:8 offset1:74
	s_waitcnt vmcnt(16)
	ds_write2_b32 v68, v142, v143 offset0:140 offset1:206
	v_add_u32_e32 v0, 0x840, v0
	v_add_u32_e32 v68, 0x400, v0
	s_waitcnt vmcnt(14)
	ds_write2_b32 v0, v144, v145 offset1:66
	s_waitcnt vmcnt(12)
	ds_write2_b32 v0, v146, v147 offset0:132 offset1:198
	s_waitcnt vmcnt(10)
	ds_write2_b32 v68, v148, v149 offset0:8 offset1:74
	s_waitcnt vmcnt(8)
	ds_write2_b32 v68, v150, v151 offset0:140 offset1:206
	v_add_u32_e32 v0, 0x840, v0
	v_add_u32_e32 v68, 0x400, v0
	s_waitcnt vmcnt(6)
	ds_write2_b32 v0, v152, v153 offset1:66
	s_waitcnt vmcnt(4)
	ds_write2_b32 v0, v154, v155 offset0:132 offset1:198
	s_waitcnt vmcnt(2)
	ds_write2_b32 v68, v156, v157 offset0:8 offset1:74
	s_waitcnt vmcnt(0)
	ds_write2_b32 v68, v158, v159 offset0:140 offset1:206
	v_add_u32_e32 v0, 0x840, v0
	s_waitcnt lgkmcnt(0)
	s_lshl_b32 s0, s8, 1
	ds_read2_b32 v[34:35], v47 offset0:33 offset1:41
	ds_read2_b32 v[36:37], v47 offset1:8
	ds_read2_b32 v[38:39], v47 offset0:66 offset1:74
	ds_read2_b32 v[40:41], v47 offset0:99 offset1:107
	ds_read2_b32 v[42:43], v47 offset0:132 offset1:140
	ds_read2_b32 v[44:45], v47 offset0:165 offset1:173
	ds_read2_b32 v[60:61], v47 offset0:198 offset1:206
	ds_read2_b32 v[62:63], v47 offset0:231 offset1:239
	s_add_i32 s0, s0, 0x7fffd000
	s_lshl_b32 s2, s8, 5
	s_and_b32 s0, s0, 0x7fffffc0
	s_and_b32 s2, s2, 0x3e0
	s_lshl_b32 s0, s0, 1
	v_or_b32_e32 v0, s2, v46
	v_lshl_add_u64 v[64:65], v[8:9], 0, s[0:1]
	v_lshlrev_b32_e32 v0, 11, v0
	s_waitcnt lgkmcnt(6)
	v_cvt_pk_bf16_f32 v30, v36, v34
	s_waitcnt lgkmcnt(4)
	v_cvt_pk_bf16_f32 v31, v38, v40
	s_waitcnt lgkmcnt(2)
	v_cvt_pk_bf16_f32 v32, v42, v44
	s_waitcnt lgkmcnt(0)
	v_cvt_pk_bf16_f32 v33, v60, v62
	v_lshl_add_u64 v[66:67], v[64:65], 0, v[0:1]
	global_store_dwordx4 v[66:67], v[30:33], off
	v_or_b32_e32 v0, s2, v48
	v_lshlrev_b32_e32 v0, 11, v0
	v_cvt_pk_bf16_f32 v30, v37, v35
	v_cvt_pk_bf16_f32 v31, v39, v41
	v_cvt_pk_bf16_f32 v32, v43, v45
	v_cvt_pk_bf16_f32 v33, v61, v63
	ds_read2_b32 v[36:37], v47 offset0:49 offset1:57
	ds_read2_b32 v[38:39], v47 offset0:16 offset1:24
	ds_read2_b32 v[40:41], v47 offset0:82 offset1:90
	ds_read2_b32 v[42:43], v47 offset0:115 offset1:123
	ds_read2_b32 v[44:45], v47 offset0:148 offset1:156
	ds_read2_b32 v[60:61], v47 offset0:181 offset1:189
	ds_read2_b32 v[62:63], v47 offset0:214 offset1:222
	ds_read2_b32 v[66:67], v47 offset0:247 offset1:255
	v_lshl_add_u64 v[34:35], v[64:65], 0, v[0:1]
	v_or_b32_e32 v0, s2, v49
	v_lshlrev_b32_e32 v0, 11, v0
	global_store_dwordx4 v[34:35], v[30:33], off
	v_lshl_add_u64 v[34:35], v[64:65], 0, v[0:1]
	v_or_b32_e32 v0, s2, v50
	s_waitcnt lgkmcnt(6)
	v_cvt_pk_bf16_f32 v30, v38, v36
	s_waitcnt lgkmcnt(4)
	v_cvt_pk_bf16_f32 v31, v40, v42
	s_waitcnt lgkmcnt(2)
	v_cvt_pk_bf16_f32 v32, v44, v60
	s_waitcnt lgkmcnt(0)
	v_cvt_pk_bf16_f32 v33, v62, v66
	v_lshlrev_b32_e32 v0, 11, v0
	global_store_dwordx4 v[34:35], v[30:33], off
	v_lshl_add_u64 v[34:35], v[64:65], 0, v[0:1]
	s_nop 0
	v_cvt_pk_bf16_f32 v30, v39, v37
	v_cvt_pk_bf16_f32 v31, v41, v43
	v_cvt_pk_bf16_f32 v32, v45, v61
	v_cvt_pk_bf16_f32 v33, v63, v67
	global_store_dwordx4 v[34:35], v[30:33], off
	s_waitcnt lgkmcnt(0)

.LBB0_321:
	v_lshl_add_u64 v[60:61], v[44:45], 0, s[2:3]
	v_lshl_add_u64 v[62:63], v[42:43], 0, s[2:3]
	v_lshl_add_u64 v[64:65], v[40:41], 0, s[2:3]
	v_lshl_add_u64 v[66:67], v[38:39], 0, s[2:3]
	v_lshl_add_u64 v[68:69], v[36:37], 0, s[2:3]
	v_lshl_add_u64 v[70:71], v[34:35], 0, s[2:3]
	v_lshl_add_u64 v[72:73], v[32:33], 0, s[2:3]
	v_lshl_add_u64 v[74:75], v[30:31], 0, s[2:3]
	global_load_dword v128, v[60:61], off nt
	s_nop 0
	global_load_dword v129, v[62:63], off nt
	s_nop 0
	global_load_dword v130, v[64:65], off nt
	global_load_dword v131, v[66:67], off nt
	s_nop 0
	global_load_dword v132, v[68:69], off nt
	global_load_dword v133, v[70:71], off nt
	global_load_dword v134, v[72:73], off nt
	global_load_dword v135, v[74:75], off nt
	s_add_u32 s2, s2, 0x10000
	s_addc_u32 s3, s3, 0
	v_lshl_add_u64 v[60:61], v[44:45], 0, s[2:3]
	v_lshl_add_u64 v[62:63], v[42:43], 0, s[2:3]
	v_lshl_add_u64 v[64:65], v[40:41], 0, s[2:3]
	v_lshl_add_u64 v[66:67], v[38:39], 0, s[2:3]
	v_lshl_add_u64 v[68:69], v[36:37], 0, s[2:3]
	v_lshl_add_u64 v[70:71], v[34:35], 0, s[2:3]
	v_lshl_add_u64 v[72:73], v[32:33], 0, s[2:3]
	v_lshl_add_u64 v[74:75], v[30:31], 0, s[2:3]
	global_load_dword v136, v[60:61], off nt
	s_nop 0
	global_load_dword v137, v[62:63], off nt
	s_nop 0
	global_load_dword v138, v[64:65], off nt
	global_load_dword v139, v[66:67], off nt
	s_nop 0
	global_load_dword v140, v[68:69], off nt
	global_load_dword v141, v[70:71], off nt
	global_load_dword v142, v[72:73], off nt
	global_load_dword v143, v[74:75], off nt
	s_add_u32 s2, s2, 0x10000
	s_addc_u32 s3, s3, 0
	v_lshl_add_u64 v[60:61], v[44:45], 0, s[2:3]
	v_lshl_add_u64 v[62:63], v[42:43], 0, s[2:3]
	v_lshl_add_u64 v[64:65], v[40:41], 0, s[2:3]
	v_lshl_add_u64 v[66:67], v[38:39], 0, s[2:3]
	v_lshl_add_u64 v[68:69], v[36:37], 0, s[2:3]
	v_lshl_add_u64 v[70:71], v[34:35], 0, s[2:3]
	v_lshl_add_u64 v[72:73], v[32:33], 0, s[2:3]
	v_lshl_add_u64 v[74:75], v[30:31], 0, s[2:3]
	global_load_dword v144, v[60:61], off nt
	s_nop 0
	global_load_dword v145, v[62:63], off nt
	s_nop 0
	global_load_dword v146, v[64:65], off nt
	global_load_dword v147, v[66:67], off nt
	s_nop 0
	global_load_dword v148, v[68:69], off nt
	global_load_dword v149, v[70:71], off nt
	global_load_dword v150, v[72:73], off nt
	global_load_dword v151, v[74:75], off nt
	s_add_u32 s2, s2, 0x10000
	s_addc_u32 s3, s3, 0
	v_lshl_add_u64 v[60:61], v[44:45], 0, s[2:3]
	v_lshl_add_u64 v[62:63], v[42:43], 0, s[2:3]
	v_lshl_add_u64 v[64:65], v[40:41], 0, s[2:3]
	v_lshl_add_u64 v[66:67], v[38:39], 0, s[2:3]
	v_lshl_add_u64 v[68:69], v[36:37], 0, s[2:3]
	v_lshl_add_u64 v[70:71], v[34:35], 0, s[2:3]
	v_lshl_add_u64 v[72:73], v[32:33], 0, s[2:3]
	v_lshl_add_u64 v[74:75], v[30:31], 0, s[2:3]
	global_load_dword v152, v[60:61], off nt
	s_nop 0
	global_load_dword v153, v[62:63], off nt
	s_nop 0
	global_load_dword v154, v[64:65], off nt
	global_load_dword v155, v[66:67], off nt
	s_nop 0
	global_load_dword v156, v[68:69], off nt
	global_load_dword v157, v[70:71], off nt
	global_load_dword v158, v[72:73], off nt
	global_load_dword v159, v[74:75], off nt
	s_add_u32 s2, s2, 0x10000
	s_addc_u32 s3, s3, 0
	v_add_u32_e32 v68, 0x400, v0
	s_waitcnt vmcnt(30)
	ds_write2_b32 v0, v128, v129 offset1:66
	s_waitcnt vmcnt(28)
	ds_write2_b32 v0, v130, v131 offset0:132 offset1:198
	s_waitcnt vmcnt(26)
	ds_write2_b32 v68, v132, v133 offset0:8 offset1:74
	s_waitcnt vmcnt(24)
	ds_write2_b32 v68, v134, v135 offset0:140 offset1:206
	v_add_u32_e32 v0, 0x840, v0
	v_add_u32_e32 v68, 0x400, v0
	s_waitcnt vmcnt(22)
	ds_write2_b32 v0, v136, v137 offset1:66
	s_waitcnt vmcnt(20)
	ds_write2_b32 v0, v138, v139 offset0:132 offset1:198
	s_waitcnt vmcnt(18)
	ds_write2_b32 v68, v140, v141 offset0:8 offset1:74
	s_waitcnt vmcnt(16)
	ds_write2_b32 v68, v142, v143 offset0:140 offset1:206
	v_add_u32_e32 v0, 0x840, v0
	v_add_u32_e32 v68, 0x400, v0
	s_waitcnt vmcnt(14)
	ds_write2_b32 v0, v144, v145 offset1:66
	s_waitcnt vmcnt(12)
	ds_write2_b32 v0, v146, v147 offset0:132 offset1:198
	s_waitcnt vmcnt(10)
	ds_write2_b32 v68, v148, v149 offset0:8 offset1:74
	s_waitcnt vmcnt(8)
	ds_write2_b32 v68, v150, v151 offset0:140 offset1:206
	v_add_u32_e32 v0, 0x840, v0
	v_add_u32_e32 v68, 0x400, v0
	s_waitcnt vmcnt(6)
	ds_write2_b32 v0, v152, v153 offset1:66
	s_waitcnt vmcnt(4)
	ds_write2_b32 v0, v154, v155 offset0:132 offset1:198
	s_waitcnt vmcnt(2)
	ds_write2_b32 v68, v156, v157 offset0:8 offset1:74
	s_waitcnt vmcnt(0)
	ds_write2_b32 v68, v158, v159 offset0:140 offset1:206
	v_add_u32_e32 v0, 0x840, v0
	s_waitcnt lgkmcnt(0)
	s_lshl_b32 s0, s8, 1
	ds_read2_b32 v[34:35], v47 offset0:33 offset1:41
	ds_read2_b32 v[36:37], v47 offset1:8
	ds_read2_b32 v[38:39], v47 offset0:66 offset1:74
	ds_read2_b32 v[40:41], v47 offset0:99 offset1:107
	ds_read2_b32 v[42:43], v47 offset0:132 offset1:140
	ds_read2_b32 v[44:45], v47 offset0:165 offset1:173
	ds_read2_b32 v[60:61], v47 offset0:198 offset1:206
	ds_read2_b32 v[62:63], v47 offset0:231 offset1:239
	s_add_i32 s0, s0, 0x7fffd200
	s_lshl_b32 s2, s8, 5
	s_and_b32 s0, s0, 0x7fffffc0
	s_and_b32 s2, s2, 0x3e0
	s_lshl_b32 s0, s0, 1
	v_or_b32_e32 v0, s2, v46
	v_lshl_add_u64 v[64:65], v[10:11], 0, s[0:1]
	v_lshlrev_b32_e32 v0, 10, v0
	s_waitcnt lgkmcnt(6)
	v_cvt_pk_bf16_f32 v30, v36, v34
	s_waitcnt lgkmcnt(4)
	v_cvt_pk_bf16_f32 v31, v38, v40
	s_waitcnt lgkmcnt(2)
	v_cvt_pk_bf16_f32 v32, v42, v44
	s_waitcnt lgkmcnt(0)
	v_cvt_pk_bf16_f32 v33, v60, v62
	v_lshl_add_u64 v[66:67], v[64:65], 0, v[0:1]
	global_store_dwordx4 v[66:67], v[30:33], off
	v_or_b32_e32 v0, s2, v48
	v_lshlrev_b32_e32 v0, 10, v0
	v_cvt_pk_bf16_f32 v30, v37, v35
	v_cvt_pk_bf16_f32 v31, v39, v41
	v_cvt_pk_bf16_f32 v32, v43, v45
	v_cvt_pk_bf16_f32 v33, v61, v63
	ds_read2_b32 v[36:37], v47 offset0:49 offset1:57
	ds_read2_b32 v[38:39], v47 offset0:16 offset1:24
	ds_read2_b32 v[40:41], v47 offset0:82 offset1:90
	ds_read2_b32 v[42:43], v47 offset0:115 offset1:123
	ds_read2_b32 v[44:45], v47 offset0:148 offset1:156
	ds_read2_b32 v[60:61], v47 offset0:181 offset1:189
	ds_read2_b32 v[62:63], v47 offset0:214 offset1:222
	ds_read2_b32 v[66:67], v47 offset0:247 offset1:255
	v_lshl_add_u64 v[34:35], v[64:65], 0, v[0:1]
	v_or_b32_e32 v0, s2, v49
	v_lshlrev_b32_e32 v0, 10, v0
	global_store_dwordx4 v[34:35], v[30:33], off
	v_lshl_add_u64 v[34:35], v[64:65], 0, v[0:1]
	v_or_b32_e32 v0, s2, v50
	s_waitcnt lgkmcnt(6)
	v_cvt_pk_bf16_f32 v30, v38, v36
	s_waitcnt lgkmcnt(4)
	v_cvt_pk_bf16_f32 v31, v40, v42
	s_waitcnt lgkmcnt(2)
	v_cvt_pk_bf16_f32 v32, v44, v60
	s_waitcnt lgkmcnt(0)
	v_cvt_pk_bf16_f32 v33, v62, v66
	v_lshlrev_b32_e32 v0, 10, v0
	global_store_dwordx4 v[34:35], v[30:33], off
	v_lshl_add_u64 v[34:35], v[64:65], 0, v[0:1]
	s_nop 0
	v_cvt_pk_bf16_f32 v30, v39, v37
	v_cvt_pk_bf16_f32 v31, v41, v43
	v_cvt_pk_bf16_f32 v32, v45, v61
	v_cvt_pk_bf16_f32 v33, v63, v67
	global_store_dwordx4 v[34:35], v[30:33], off
	s_waitcnt lgkmcnt(0)

.LBB0_326:
	v_lshl_add_u64 v[60:61], v[44:45], 0, s[6:7]
	v_lshl_add_u64 v[62:63], v[42:43], 0, s[6:7]
	v_lshl_add_u64 v[64:65], v[40:41], 0, s[6:7]
	v_lshl_add_u64 v[66:67], v[38:39], 0, s[6:7]
	v_lshl_add_u64 v[68:69], v[36:37], 0, s[6:7]
	v_lshl_add_u64 v[70:71], v[34:35], 0, s[6:7]
	v_lshl_add_u64 v[72:73], v[32:33], 0, s[6:7]
	v_lshl_add_u64 v[74:75], v[30:31], 0, s[6:7]
	global_load_dword v128, v[60:61], off nt
	s_nop 0
	global_load_dword v129, v[62:63], off nt
	s_nop 0
	global_load_dword v130, v[64:65], off nt
	global_load_dword v131, v[66:67], off nt
	s_nop 0
	global_load_dword v132, v[68:69], off nt
	global_load_dword v133, v[70:71], off nt
	global_load_dword v134, v[72:73], off nt
	global_load_dword v135, v[74:75], off nt
	s_add_u32 s6, s6, 0xb8000
	s_addc_u32 s7, s7, 0
	v_lshl_add_u64 v[60:61], v[44:45], 0, s[6:7]
	v_lshl_add_u64 v[62:63], v[42:43], 0, s[6:7]
	v_lshl_add_u64 v[64:65], v[40:41], 0, s[6:7]
	v_lshl_add_u64 v[66:67], v[38:39], 0, s[6:7]
	v_lshl_add_u64 v[68:69], v[36:37], 0, s[6:7]
	v_lshl_add_u64 v[70:71], v[34:35], 0, s[6:7]
	v_lshl_add_u64 v[72:73], v[32:33], 0, s[6:7]
	v_lshl_add_u64 v[74:75], v[30:31], 0, s[6:7]
	global_load_dword v136, v[60:61], off nt
	s_nop 0
	global_load_dword v137, v[62:63], off nt
	s_nop 0
	global_load_dword v138, v[64:65], off nt
	global_load_dword v139, v[66:67], off nt
	s_nop 0
	global_load_dword v140, v[68:69], off nt
	global_load_dword v141, v[70:71], off nt
	global_load_dword v142, v[72:73], off nt
	global_load_dword v143, v[74:75], off nt
	s_add_u32 s6, s6, 0xb8000
	s_addc_u32 s7, s7, 0
	v_lshl_add_u64 v[60:61], v[44:45], 0, s[6:7]
	v_lshl_add_u64 v[62:63], v[42:43], 0, s[6:7]
	v_lshl_add_u64 v[64:65], v[40:41], 0, s[6:7]
	v_lshl_add_u64 v[66:67], v[38:39], 0, s[6:7]
	v_lshl_add_u64 v[68:69], v[36:37], 0, s[6:7]
	v_lshl_add_u64 v[70:71], v[34:35], 0, s[6:7]
	v_lshl_add_u64 v[72:73], v[32:33], 0, s[6:7]
	v_lshl_add_u64 v[74:75], v[30:31], 0, s[6:7]
	global_load_dword v144, v[60:61], off nt
	s_nop 0
	global_load_dword v145, v[62:63], off nt
	s_nop 0
	global_load_dword v146, v[64:65], off nt
	global_load_dword v147, v[66:67], off nt
	s_nop 0
	global_load_dword v148, v[68:69], off nt
	global_load_dword v149, v[70:71], off nt
	global_load_dword v150, v[72:73], off nt
	global_load_dword v151, v[74:75], off nt
	s_add_u32 s6, s6, 0xb8000
	s_addc_u32 s7, s7, 0
	v_lshl_add_u64 v[60:61], v[44:45], 0, s[6:7]
	v_lshl_add_u64 v[62:63], v[42:43], 0, s[6:7]
	v_lshl_add_u64 v[64:65], v[40:41], 0, s[6:7]
	v_lshl_add_u64 v[66:67], v[38:39], 0, s[6:7]
	v_lshl_add_u64 v[68:69], v[36:37], 0, s[6:7]
	v_lshl_add_u64 v[70:71], v[34:35], 0, s[6:7]
	v_lshl_add_u64 v[72:73], v[32:33], 0, s[6:7]
	v_lshl_add_u64 v[74:75], v[30:31], 0, s[6:7]
	global_load_dword v152, v[60:61], off nt
	s_nop 0
	global_load_dword v153, v[62:63], off nt
	s_nop 0
	global_load_dword v154, v[64:65], off nt
	global_load_dword v155, v[66:67], off nt
	s_nop 0
	global_load_dword v156, v[68:69], off nt
	global_load_dword v157, v[70:71], off nt
	global_load_dword v158, v[72:73], off nt
	global_load_dword v159, v[74:75], off nt
	s_add_u32 s6, s6, 0xb8000
	s_addc_u32 s7, s7, 0
	v_add_u32_e32 v68, 0x400, v0
	s_waitcnt vmcnt(30)
	ds_write2_b32 v0, v128, v129 offset1:66
	s_waitcnt vmcnt(28)
	ds_write2_b32 v0, v130, v131 offset0:132 offset1:198
	s_waitcnt vmcnt(26)
	ds_write2_b32 v68, v132, v133 offset0:8 offset1:74
	s_waitcnt vmcnt(24)
	ds_write2_b32 v68, v134, v135 offset0:140 offset1:206
	v_add_u32_e32 v0, 0x840, v0
	v_add_u32_e32 v68, 0x400, v0
	s_waitcnt vmcnt(22)
	ds_write2_b32 v0, v136, v137 offset1:66
	s_waitcnt vmcnt(20)
	ds_write2_b32 v0, v138, v139 offset0:132 offset1:198
	s_waitcnt vmcnt(18)
	ds_write2_b32 v68, v140, v141 offset0:8 offset1:74
	s_waitcnt vmcnt(16)
	ds_write2_b32 v68, v142, v143 offset0:140 offset1:206
	v_add_u32_e32 v0, 0x840, v0
	v_add_u32_e32 v68, 0x400, v0
	s_waitcnt vmcnt(14)
	ds_write2_b32 v0, v144, v145 offset1:66
	s_waitcnt vmcnt(12)
	ds_write2_b32 v0, v146, v147 offset0:132 offset1:198
	s_waitcnt vmcnt(10)
	ds_write2_b32 v68, v148, v149 offset0:8 offset1:74
	s_waitcnt vmcnt(8)
	ds_write2_b32 v68, v150, v151 offset0:140 offset1:206
	v_add_u32_e32 v0, 0x840, v0
	v_add_u32_e32 v68, 0x400, v0
	s_waitcnt vmcnt(6)
	ds_write2_b32 v0, v152, v153 offset1:66
	s_waitcnt vmcnt(4)
	ds_write2_b32 v0, v154, v155 offset0:132 offset1:198
	s_waitcnt vmcnt(2)
	ds_write2_b32 v68, v156, v157 offset0:8 offset1:74
	s_waitcnt vmcnt(0)
	ds_write2_b32 v68, v158, v159 offset0:140 offset1:206
	v_add_u32_e32 v0, 0x840, v0
	s_waitcnt lgkmcnt(0)
	ds_read2_b32 v[34:35], v47 offset0:33 offset1:41
	ds_read2_b32 v[36:37], v47 offset1:8
	ds_read2_b32 v[38:39], v47 offset0:66 offset1:74
	ds_read2_b32 v[40:41], v47 offset0:99 offset1:107
	ds_read2_b32 v[42:43], v47 offset0:132 offset1:140
	ds_read2_b32 v[44:45], v47 offset0:165 offset1:173
	ds_read2_b32 v[60:61], v47 offset0:198 offset1:206
	ds_read2_b32 v[62:63], v47 offset0:231 offset1:239
	v_or_b32_e32 v66, s2, v46
	v_ashrrev_i32_e32 v67, 31, v66
	v_lshl_add_u64 v[64:65], s[4:5], 1, v[12:13]
	v_lshlrev_b64 v[66:67], 11, v[66:67]
	s_waitcnt lgkmcnt(6)
	v_cvt_pk_bf16_f32 v30, v36, v34
	s_waitcnt lgkmcnt(4)
	v_cvt_pk_bf16_f32 v31, v38, v40
	s_waitcnt lgkmcnt(2)
	v_cvt_pk_bf16_f32 v32, v42, v44
	s_waitcnt lgkmcnt(0)
	v_cvt_pk_bf16_f32 v33, v60, v62
	v_lshl_add_u64 v[66:67], v[64:65], 0, v[66:67]
	v_or_b32_e32 v34, s2, v48
	global_store_dwordx4 v[66:67], v[30:33], off
	s_nop 1
	v_cvt_pk_bf16_f32 v30, v37, v35
	v_ashrrev_i32_e32 v35, 31, v34
	v_cvt_pk_bf16_f32 v31, v39, v41
	v_cvt_pk_bf16_f32 v32, v43, v45
	v_cvt_pk_bf16_f32 v33, v61, v63
	v_lshlrev_b64 v[34:35], 11, v[34:35]
	ds_read2_b32 v[36:37], v47 offset0:49 offset1:57
	ds_read2_b32 v[38:39], v47 offset0:16 offset1:24
	ds_read2_b32 v[40:41], v47 offset0:82 offset1:90
	ds_read2_b32 v[42:43], v47 offset0:115 offset1:123
	ds_read2_b32 v[44:45], v47 offset0:148 offset1:156
	ds_read2_b32 v[60:61], v47 offset0:181 offset1:189
	ds_read2_b32 v[62:63], v47 offset0:214 offset1:222
	ds_read2_b32 v[66:67], v47 offset0:247 offset1:255
	v_lshl_add_u64 v[34:35], v[64:65], 0, v[34:35]
	global_store_dwordx4 v[34:35], v[30:33], off
	v_or_b32_e32 v34, s2, v49
	v_ashrrev_i32_e32 v35, 31, v34
	v_lshlrev_b64 v[34:35], 11, v[34:35]
	s_waitcnt lgkmcnt(6)
	v_cvt_pk_bf16_f32 v30, v38, v36
	s_waitcnt lgkmcnt(4)
	v_cvt_pk_bf16_f32 v31, v40, v42
	s_waitcnt lgkmcnt(2)
	v_cvt_pk_bf16_f32 v32, v44, v60
	s_waitcnt lgkmcnt(0)
	v_cvt_pk_bf16_f32 v33, v62, v66
	v_lshl_add_u64 v[34:35], v[64:65], 0, v[34:35]
	global_store_dwordx4 v[34:35], v[30:33], off
	v_or_b32_e32 v34, s2, v50
	v_ashrrev_i32_e32 v35, 31, v34
	v_lshlrev_b64 v[34:35], 11, v[34:35]
	v_cvt_pk_bf16_f32 v30, v39, v37
	v_cvt_pk_bf16_f32 v31, v41, v43
	v_cvt_pk_bf16_f32 v32, v45, v61
	v_cvt_pk_bf16_f32 v33, v63, v67
	v_lshl_add_u64 v[34:35], v[64:65], 0, v[34:35]
	global_store_dwordx4 v[34:35], v[30:33], off
	s_waitcnt lgkmcnt(0)
	s_branch .LBB0_295
